# compress K loop: reissue each weight load right behind the MFMA that frees its registers (16 loads always in flight)
# baseline (speedup 1.0000x reference)
; __device__ __forceinline__ int mk_ltid() { int t = threadIdx.x; asm volatile("" : "+v"(t)); return t; }
; #define LAS __attribute__((address_space(3)))
; __device__ __forceinline__ void compress_unit(LAS unsigned char* lds, int u, const bf16_t* QKV, const float* pe_k, const float* pe_v,
;                                               const bf16_t* CW1  , const bf16_t* CW2  , bf16_t* KCMP, bf16_t* VCMP) {
;     const int tid = mk_ltid(), lane = tid & 63, w = __builtin_amdgcn_readfirstlane(tid >> 6), r32 = lane & 31, hi = lane >> 5;
;     const int kv = u >> 6, b = (u >> 4) & 3, g = (u >> 3) & 1, ch = u & 7;
;     const float* pe = kv ? pe_v : pe_k;
;     const bf16_t* W1 = CW1 + (size_t)kv * 256 * 2048; const bf16_t* W2 = CW2 + (size_t)kv * 64 * 256;
;     bf16_t* OUT = (kv ? VCMP : KCMP) + (size_t)((b * 2 + g) * 256 + ch * 32) * 64;
;     const int n = ch * 32 + r32;
;     const bf16_t* Ag = QKV + (size_t)(b * SEQ + 16 * n) * EVEN_PAD + (kv ? E_VC : E_KC) + g * 64 + hi * 8;
;     const bf16_t* Bg = W1 + (size_t)(32 * w + r32) * 2048 + hi * 8;
;     LAS bf16_t* HID = (LAS bf16_t*)lds;
;     LAS float* PE = (LAS float*)(lds + 20480);
;     v16f acc;
; #pragma unroll
;     for (int r = 0; r < 16; ++r) acc[r] = 0.f;
;     __syncthreads();
;     *(LAS v4f*)(PE + tid * 4) = *(const v4f*)(pe + tid * 4);
;     __syncthreads();
; #pragma unroll 8
;     for (int st = 0; st < 128; ++st) {
;         const int li = st >> 2, d0 = (st & 3) * 16;
;         const v4u ar = *(const v4u*)(Ag + (size_t)li * EVEN_PAD + d0);
;         const v4f pa = *(const LAS v4f*)(PE + li * 64 + d0 + hi * 8), pb = *(const LAS v4f*)(PE + li * 64 + d0 + hi * 8 + 4);
;         const v8s bfr = *(const v8s*)(Bg + st * 16);
;         v4u aw;
;         aw.x = pkbf(__uint_as_float(ar.x << 16) + pa.x, __uint_as_float(ar.x & 0xffff0000u) + pa.y);
;         aw.y = pkbf(__uint_as_float(ar.y << 16) + pa.z, __uint_as_float(ar.y & 0xffff0000u) + pa.w);
;         aw.z = pkbf(__uint_as_float(ar.z << 16) + pb.x, __uint_as_float(ar.z & 0xffff0000u) + pb.y);
;         aw.w = pkbf(__uint_as_float(ar.w << 16) + pb.z, __uint_as_float(ar.w & 0xffff0000u) + pb.w);
.LBB0_411:
	v_mov_b32_e32 v0, v202
	s_ashr_i32 s12, s18, 6
	v_readfirstlane_b32 s10, v0
	s_ashr_i32 s29, s10, 6
	s_bfe_u32 s11, s18, 0x20004
	s_ashr_i32 s13, s12, 31
	s_lshl_b32 s10, s18, 5
	s_lshr_b32 s28, s18, 3
	s_lshl_b64 s[16:17], s[12:13], 20
	s_and_b32 s27, s10, 0xe0
	s_lshl_b32 s30, s11, 12
	s_lshl_b32 s10, s29, 5
	v_and_b32_e32 v41, 31, v0
	s_cmp_lt_u32 s18, 64
	s_cselect_b64 s[14:15], -1, 0
	v_or_b32_e32 v2, s27, v41
	v_lshl_or_b32 v2, v2, 4, s30
	s_and_b64 s[30:31], s[14:15], exec
	s_cselect_b32 s30, s4, s6
	s_movk_i32 s34, 0x1400
	v_mul_u32_u24_e32 v6, 0xe00, v2
	s_cselect_b32 s31, s5, s7
	s_cselect_b32 s34, s34, 0x1500
	s_add_u32 s30, s30, s8
	v_lshlrev_b32_e32 v2, 2, v0
	s_addc_u32 s31, s31, s9
	v_ashrrev_i32_e32 v3, 31, v2
	v_lshl_add_u64 v[2:3], v[2:3], 2, s[30:31]
	s_barrier
	global_load_dwordx4 v[2:5], v[2:3], off
	v_bfe_u32 v40, v0, 5, 1
	v_readlane_b32 s30, v254, 61
	v_lshl_add_u32 v0, v0, 4, 0
	v_or_b32_e32 v34, s10, v41
	v_lshl_add_u32 v42, v40, 5, s30
	s_lshl_b32 s30, s18, 4
	s_and_b32 s30, s30, 0x80
	s_or_b32 s30, s30, s34
	s_add_u32 s30, s0, s30
	s_addc_u32 s31, s1, 0
	v_ashrrev_i32_e32 v35, 31, v34
	s_add_u32 s16, s25, s16
	s_addc_u32 s17, s26, s17
	s_waitcnt vmcnt(0)
	ds_write_b128 v0, v[2:5] offset:20480
	v_lshlrev_b32_e32 v2, 1, v6
	v_mov_b32_e32 v3, v1
	v_lshl_add_u64 v[36:37], s[30:31], 0, v[2:3]
	v_lshlrev_b64 v[2:3], 12, v[34:35]
	v_lshl_add_u64 v[38:39], s[16:17], 0, v[2:3]
	v_mov_b32_e32 v2, 0
	v_lshlrev_b32_e32 v0, 4, v40
	s_mov_b32 s16, 0
	v_mov_b32_e32 v3, v2
	v_mov_b32_e32 v4, v2
	v_mov_b32_e32 v5, v2
	v_mov_b32_e32 v6, v2
	v_mov_b32_e32 v7, v2
	v_mov_b32_e32 v8, v2
	v_mov_b32_e32 v9, v2
	v_mov_b32_e32 v10, v2
	v_mov_b32_e32 v11, v2
	v_mov_b32_e32 v12, v2
	v_mov_b32_e32 v13, v2
	v_mov_b32_e32 v14, v2
	v_mov_b32_e32 v15, v2
	v_mov_b32_e32 v16, v2
	v_mov_b32_e32 v17, v2
	s_waitcnt lgkmcnt(0)
	s_barrier
	v_and_b32_e32 v64, 63, v202
	v_and_b32_e32 v65, 7, v64
	v_lshrrev_b32_e32 v64, 3, v64
	s_lshr_b32 s17, s10, 5
	s_lshl_b32 s34, s17, 6
	v_add_u32_e32 v66, s34, v64
	v_mul_u32_u24_e32 v66, 0x1c00, v66
	v_lshl_add_u32 v66, v65, 4, v66
	s_mul_i32 s34, s17, 0x4040
	s_add_i32 s34, s34, 28672
	v_lshlrev_b32_e32 v67, 7, v64
	v_lshl_add_u32 v67, v65, 4, v67
	v_add_u32_e32 v67, s34, v67
	v_lshlrev_b32_e32 v68, 8, v64
	v_lshl_add_u32 v68, v65, 5, v68
	v_add_u32_e32 v68, 0x5000, v68
	s_bfe_u32 s35, s18, 0x20004
	s_lshl_b32 s35, s35, 12
	s_and_b32 s36, s18, 7
	s_lshl_b32 s36, s36, 9
	s_add_i32 s35, s35, s36
	s_mul_i32 s35, s35, 0x1c00
	s_add_u32 s44, s30, s35
	s_addc_u32 s45, s31, 0
	s_add_u32 s44, s44, 0x1c800000
	s_addc_u32 s45, s45, 0
	global_load_dwordx4 v[104:107], v66, s[44:45]
	s_add_u32 s46, s44, 0xe000
	s_addc_u32 s47, s45, 0
	global_load_dwordx4 v[108:111], v66, s[46:47]
	s_add_u32 s46, s44, 0x1c000
	s_addc_u32 s47, s45, 0
	global_load_dwordx4 v[112:115], v66, s[46:47]
	s_add_u32 s46, s44, 0x2a000
	s_addc_u32 s47, s45, 0
	global_load_dwordx4 v[116:119], v66, s[46:47]
	s_add_u32 s46, s44, 0x1c000
	s_addc_u32 s47, s45, 0
	global_load_dwordx4 v[120:123], v66, s[46:47]
	s_add_u32 s46, s44, 0x2a000
	s_addc_u32 s47, s45, 0
	global_load_dwordx4 v[124:127], v66, s[46:47]
	s_add_u32 s46, s44, 0x38000
	s_addc_u32 s47, s45, 0
	global_load_dwordx4 v[128:131], v66, s[46:47]
	s_add_u32 s46, s44, 0x46000
	s_addc_u32 s47, s45, 0
	global_load_dwordx4 v[132:135], v66, s[46:47]
	s_add_u32 s46, s44, 0x38000
	s_addc_u32 s47, s45, 0
	global_load_dwordx4 v[136:139], v66, s[46:47]
	s_add_u32 s46, s44, 0x46000
	s_addc_u32 s47, s45, 0
	global_load_dwordx4 v[140:143], v66, s[46:47]
	s_add_u32 s46, s44, 0x54000
	s_addc_u32 s47, s45, 0
	global_load_dwordx4 v[144:147], v66, s[46:47]
	s_add_u32 s46, s44, 0x62000
	s_addc_u32 s47, s45, 0
	global_load_dwordx4 v[148:151], v66, s[46:47]
	s_add_u32 s46, s44, 0x54000
	s_addc_u32 s47, s45, 0
	global_load_dwordx4 v[152:155], v66, s[46:47]
	s_add_u32 s46, s44, 0x62000
	s_addc_u32 s47, s45, 0
	global_load_dwordx4 v[156:159], v66, s[46:47]
	s_add_u32 s46, s44, 0x70000
	s_addc_u32 s47, s45, 0
	global_load_dwordx4 v[160:163], v66, s[46:47]
	s_add_u32 s46, s44, 0x7e000
	s_addc_u32 s47, s45, 0
	global_load_dwordx4 v[164:167], v66, s[46:47]
	ds_read_b128 v[72:75], v68
	ds_read_b128 v[76:79], v68 offset:16
	ds_read_b128 v[80:83], v68 offset:2048
	ds_read_b128 v[84:87], v68 offset:2064
	ds_read_b128 v[88:91], v68 offset:4096
	ds_read_b128 v[92:95], v68 offset:4112
	ds_read_b128 v[96:99], v68 offset:6144
	ds_read_b128 v[100:103], v68 offset:6160
	s_waitcnt lgkmcnt(0)
	s_waitcnt vmcnt(15)
	v_lshlrev_b32_e32 v168, 16, v104
	v_and_b32_e32 v169, 0xffff0000, v104
	v_lshlrev_b32_e32 v170, 16, v105
	v_and_b32_e32 v171, 0xffff0000, v105
	v_pk_add_f32 v[168:169], v[72:73], v[168:169]
	v_pk_add_f32 v[170:171], v[74:75], v[170:171]
	v_cvt_pk_bf16_f32 v104, v168, v169
	v_cvt_pk_bf16_f32 v105, v170, v171
	v_lshlrev_b32_e32 v168, 16, v106
	v_and_b32_e32 v169, 0xffff0000, v106
	v_lshlrev_b32_e32 v170, 16, v107
	v_and_b32_e32 v171, 0xffff0000, v107
	v_pk_add_f32 v[168:169], v[76:77], v[168:169]
	v_pk_add_f32 v[170:171], v[78:79], v[170:171]
	v_cvt_pk_bf16_f32 v106, v168, v169
	v_cvt_pk_bf16_f32 v107, v170, v171
	ds_write_b128 v67, v[104:107]
	s_waitcnt vmcnt(14)
	v_lshlrev_b32_e32 v168, 16, v108
	v_and_b32_e32 v169, 0xffff0000, v108
	v_lshlrev_b32_e32 v170, 16, v109
	v_and_b32_e32 v171, 0xffff0000, v109
	v_pk_add_f32 v[168:169], v[80:81], v[168:169]
	v_pk_add_f32 v[170:171], v[82:83], v[170:171]
	v_cvt_pk_bf16_f32 v108, v168, v169
	v_cvt_pk_bf16_f32 v109, v170, v171
	v_lshlrev_b32_e32 v168, 16, v110
	v_and_b32_e32 v169, 0xffff0000, v110
	v_lshlrev_b32_e32 v170, 16, v111
	v_and_b32_e32 v171, 0xffff0000, v111
	v_pk_add_f32 v[168:169], v[84:85], v[168:169]
	v_pk_add_f32 v[170:171], v[86:87], v[170:171]
	v_cvt_pk_bf16_f32 v110, v168, v169
	v_cvt_pk_bf16_f32 v111, v170, v171
	ds_write_b128 v67, v[108:111] offset:1024
	s_waitcnt vmcnt(13)
; #define LAS __attribute__((address_space(3)))
; __device__ __forceinline__ void compress_unit(LAS unsigned char* lds, int u, const bf16_t* QKV, const float* pe_k, const float* pe_v,
;                                               const bf16_t* CW1  , const bf16_t* CW2  , bf16_t* KCMP, bf16_t* VCMP) {
;     ...
;     for (int st = 0; st < 128; ++st) {
;         const int li = st >> 2, d0 = (st & 3) * 16;
;         const v4u ar = *(const v4u*)(Ag + (size_t)li * EVEN_PAD + d0);
;         const v4f pa = *(const LAS v4f*)(PE + li * 64 + d0 + hi * 8), pb = *(const LAS v4f*)(PE + li * 64 + d0 + hi * 8 + 4);
;         const v8s bfr = *(const v8s*)(Bg + st * 16);
;         v4u aw;
;         aw.x = pkbf(__uint_as_float(ar.x << 16) + pa.x, __uint_as_float(ar.x & 0xffff0000u) + pa.y);
;         aw.y = pkbf(__uint_as_float(ar.y << 16) + pa.z, __uint_as_float(ar.y & 0xffff0000u) + pa.w);
;         aw.z = pkbf(__uint_as_float(ar.z << 16) + pb.x, __uint_as_float(ar.z & 0xffff0000u) + pb.y);
;         aw.w = pkbf(__uint_as_float(ar.w << 16) + pb.z, __uint_as_float(ar.w & 0xffff0000u) + pb.w);
	v_lshlrev_b32_e32 v168, 16, v112
	v_and_b32_e32 v169, 0xffff0000, v112
	v_lshlrev_b32_e32 v170, 16, v113
	v_and_b32_e32 v171, 0xffff0000, v113
	v_pk_add_f32 v[168:169], v[88:89], v[168:169]
	v_pk_add_f32 v[170:171], v[90:91], v[170:171]
	v_cvt_pk_bf16_f32 v112, v168, v169
	v_cvt_pk_bf16_f32 v113, v170, v171
	v_lshlrev_b32_e32 v168, 16, v114
	v_and_b32_e32 v169, 0xffff0000, v114
	v_lshlrev_b32_e32 v170, 16, v115
	v_and_b32_e32 v171, 0xffff0000, v115
	v_pk_add_f32 v[168:169], v[92:93], v[168:169]
	v_pk_add_f32 v[170:171], v[94:95], v[170:171]
	v_cvt_pk_bf16_f32 v114, v168, v169
	v_cvt_pk_bf16_f32 v115, v170, v171
	ds_write_b128 v67, v[112:115] offset:2048
	s_waitcnt vmcnt(12)
	v_lshlrev_b32_e32 v168, 16, v116
	v_and_b32_e32 v169, 0xffff0000, v116
	v_lshlrev_b32_e32 v170, 16, v117
	v_and_b32_e32 v171, 0xffff0000, v117
	v_pk_add_f32 v[168:169], v[96:97], v[168:169]
	v_pk_add_f32 v[170:171], v[98:99], v[170:171]
	v_cvt_pk_bf16_f32 v116, v168, v169
	v_cvt_pk_bf16_f32 v117, v170, v171
	v_lshlrev_b32_e32 v168, 16, v118
	v_and_b32_e32 v169, 0xffff0000, v118
	v_lshlrev_b32_e32 v170, 16, v119
	v_and_b32_e32 v171, 0xffff0000, v119
	v_pk_add_f32 v[168:169], v[100:101], v[168:169]
	v_pk_add_f32 v[170:171], v[102:103], v[170:171]
	v_cvt_pk_bf16_f32 v118, v168, v169
	v_cvt_pk_bf16_f32 v119, v170, v171
	ds_write_b128 v67, v[116:119] offset:3072
	s_waitcnt vmcnt(11)
	v_lshlrev_b32_e32 v168, 16, v120
	v_and_b32_e32 v169, 0xffff0000, v120
	v_lshlrev_b32_e32 v170, 16, v121
	v_and_b32_e32 v171, 0xffff0000, v121
	v_pk_add_f32 v[168:169], v[72:73], v[168:169]
	v_pk_add_f32 v[170:171], v[74:75], v[170:171]
	v_cvt_pk_bf16_f32 v120, v168, v169
	v_cvt_pk_bf16_f32 v121, v170, v171
	v_lshlrev_b32_e32 v168, 16, v122
	v_and_b32_e32 v169, 0xffff0000, v122
	v_lshlrev_b32_e32 v170, 16, v123
	v_and_b32_e32 v171, 0xffff0000, v123
	v_pk_add_f32 v[168:169], v[76:77], v[168:169]
	v_pk_add_f32 v[170:171], v[78:79], v[170:171]
	v_cvt_pk_bf16_f32 v122, v168, v169
	v_cvt_pk_bf16_f32 v123, v170, v171
	ds_write_b128 v67, v[120:123] offset:4112
	s_waitcnt vmcnt(10)
	v_lshlrev_b32_e32 v168, 16, v124
	v_and_b32_e32 v169, 0xffff0000, v124
	v_lshlrev_b32_e32 v170, 16, v125
	v_and_b32_e32 v171, 0xffff0000, v125
	v_pk_add_f32 v[168:169], v[80:81], v[168:169]
	v_pk_add_f32 v[170:171], v[82:83], v[170:171]
	v_cvt_pk_bf16_f32 v124, v168, v169
	v_cvt_pk_bf16_f32 v125, v170, v171
	v_lshlrev_b32_e32 v168, 16, v126
	v_and_b32_e32 v169, 0xffff0000, v126
	v_lshlrev_b32_e32 v170, 16, v127
	v_and_b32_e32 v171, 0xffff0000, v127
	v_pk_add_f32 v[168:169], v[84:85], v[168:169]
	v_pk_add_f32 v[170:171], v[86:87], v[170:171]
	v_cvt_pk_bf16_f32 v126, v168, v169
	v_cvt_pk_bf16_f32 v127, v170, v171
	ds_write_b128 v67, v[124:127] offset:5136
	s_waitcnt vmcnt(9)
	v_lshlrev_b32_e32 v168, 16, v128
	v_and_b32_e32 v169, 0xffff0000, v128
	v_lshlrev_b32_e32 v170, 16, v129
	v_and_b32_e32 v171, 0xffff0000, v129
	v_pk_add_f32 v[168:169], v[88:89], v[168:169]
	v_pk_add_f32 v[170:171], v[90:91], v[170:171]
	v_cvt_pk_bf16_f32 v128, v168, v169
	v_cvt_pk_bf16_f32 v129, v170, v171
	v_lshlrev_b32_e32 v168, 16, v130
	v_and_b32_e32 v169, 0xffff0000, v130
	v_lshlrev_b32_e32 v170, 16, v131
	v_and_b32_e32 v171, 0xffff0000, v131
	v_pk_add_f32 v[168:169], v[92:93], v[168:169]
	v_pk_add_f32 v[170:171], v[94:95], v[170:171]
	v_cvt_pk_bf16_f32 v130, v168, v169
	v_cvt_pk_bf16_f32 v131, v170, v171
	ds_write_b128 v67, v[128:131] offset:6160
	s_waitcnt vmcnt(8)
	v_lshlrev_b32_e32 v168, 16, v132
	v_and_b32_e32 v169, 0xffff0000, v132
	v_lshlrev_b32_e32 v170, 16, v133
	v_and_b32_e32 v171, 0xffff0000, v133
	v_pk_add_f32 v[168:169], v[96:97], v[168:169]
	v_pk_add_f32 v[170:171], v[98:99], v[170:171]
	v_cvt_pk_bf16_f32 v132, v168, v169
	v_cvt_pk_bf16_f32 v133, v170, v171
	v_lshlrev_b32_e32 v168, 16, v134
	v_and_b32_e32 v169, 0xffff0000, v134
	v_lshlrev_b32_e32 v170, 16, v135
	v_and_b32_e32 v171, 0xffff0000, v135
	v_pk_add_f32 v[168:169], v[100:101], v[168:169]
	v_pk_add_f32 v[170:171], v[102:103], v[170:171]
	v_cvt_pk_bf16_f32 v134, v168, v169
	v_cvt_pk_bf16_f32 v135, v170, v171
	ds_write_b128 v67, v[132:135] offset:7184
	s_waitcnt vmcnt(7)
	v_lshlrev_b32_e32 v168, 16, v136
	v_and_b32_e32 v169, 0xffff0000, v136
	v_lshlrev_b32_e32 v170, 16, v137
	v_and_b32_e32 v171, 0xffff0000, v137
	v_pk_add_f32 v[168:169], v[72:73], v[168:169]
	v_pk_add_f32 v[170:171], v[74:75], v[170:171]
	v_cvt_pk_bf16_f32 v136, v168, v169
	v_cvt_pk_bf16_f32 v137, v170, v171
	v_lshlrev_b32_e32 v168, 16, v138
	v_and_b32_e32 v169, 0xffff0000, v138
	v_lshlrev_b32_e32 v170, 16, v139
	v_and_b32_e32 v171, 0xffff0000, v139
	v_pk_add_f32 v[168:169], v[76:77], v[168:169]
	v_pk_add_f32 v[170:171], v[78:79], v[170:171]
	v_cvt_pk_bf16_f32 v138, v168, v169
	v_cvt_pk_bf16_f32 v139, v170, v171
	ds_write_b128 v67, v[136:139] offset:8224
	s_waitcnt vmcnt(6)
	v_lshlrev_b32_e32 v168, 16, v140
	v_and_b32_e32 v169, 0xffff0000, v140
	v_lshlrev_b32_e32 v170, 16, v141
	v_and_b32_e32 v171, 0xffff0000, v141
	v_pk_add_f32 v[168:169], v[80:81], v[168:169]
	v_pk_add_f32 v[170:171], v[82:83], v[170:171]
	v_cvt_pk_bf16_f32 v140, v168, v169
	v_cvt_pk_bf16_f32 v141, v170, v171
	v_lshlrev_b32_e32 v168, 16, v142
	v_and_b32_e32 v169, 0xffff0000, v142
	v_lshlrev_b32_e32 v170, 16, v143
	v_and_b32_e32 v171, 0xffff0000, v143
	v_pk_add_f32 v[168:169], v[84:85], v[168:169]
	v_pk_add_f32 v[170:171], v[86:87], v[170:171]
	v_cvt_pk_bf16_f32 v142, v168, v169
	v_cvt_pk_bf16_f32 v143, v170, v171
	ds_write_b128 v67, v[140:143] offset:9248
	s_waitcnt vmcnt(5)
; #define LAS __attribute__((address_space(3)))
; __device__ __forceinline__ v16f mfma32(v8s a, v8s b, v16f c) { return __builtin_amdgcn_mfma_f32_32x32x16_bf16(a, b, c, 0, 0, 0); }
; __device__ __forceinline__ void compress_unit(LAS unsigned char* lds, int u, const bf16_t* QKV, const float* pe_k, const float* pe_v,
;                                               const bf16_t* CW1  , const bf16_t* CW2  , bf16_t* KCMP, bf16_t* VCMP) {
;     ...
;     for (int st = 0; st < 128; ++st) {
;         const int li = st >> 2, d0 = (st & 3) * 16;
;         const v4u ar = *(const v4u*)(Ag + (size_t)li * EVEN_PAD + d0);
;         const v4f pa = *(const LAS v4f*)(PE + li * 64 + d0 + hi * 8), pb = *(const LAS v4f*)(PE + li * 64 + d0 + hi * 8 + 4);
;         const v8s bfr = *(const v8s*)(Bg + st * 16);
;         v4u aw;
;         aw.x = pkbf(__uint_as_float(ar.x << 16) + pa.x, __uint_as_float(ar.x & 0xffff0000u) + pa.y);
;         aw.y = pkbf(__uint_as_float(ar.y << 16) + pa.z, __uint_as_float(ar.y & 0xffff0000u) + pa.w);
;         aw.z = pkbf(__uint_as_float(ar.z << 16) + pb.x, __uint_as_float(ar.z & 0xffff0000u) + pb.y);
;         aw.w = pkbf(__uint_as_float(ar.w << 16) + pb.z, __uint_as_float(ar.w & 0xffff0000u) + pb.w);
;         acc = mfma32(__builtin_bit_cast(v8s, aw), bfr, acc);
	v_lshlrev_b32_e32 v168, 16, v144
	v_and_b32_e32 v169, 0xffff0000, v144
	v_lshlrev_b32_e32 v170, 16, v145
	v_and_b32_e32 v171, 0xffff0000, v145
	v_pk_add_f32 v[168:169], v[88:89], v[168:169]
	v_pk_add_f32 v[170:171], v[90:91], v[170:171]
	v_cvt_pk_bf16_f32 v144, v168, v169
	v_cvt_pk_bf16_f32 v145, v170, v171
	v_lshlrev_b32_e32 v168, 16, v146
	v_and_b32_e32 v169, 0xffff0000, v146
	v_lshlrev_b32_e32 v170, 16, v147
	v_and_b32_e32 v171, 0xffff0000, v147
	v_pk_add_f32 v[168:169], v[92:93], v[168:169]
	v_pk_add_f32 v[170:171], v[94:95], v[170:171]
	v_cvt_pk_bf16_f32 v146, v168, v169
	v_cvt_pk_bf16_f32 v147, v170, v171
	ds_write_b128 v67, v[144:147] offset:10272
	s_waitcnt vmcnt(4)
	v_lshlrev_b32_e32 v168, 16, v148
	v_and_b32_e32 v169, 0xffff0000, v148
	v_lshlrev_b32_e32 v170, 16, v149
	v_and_b32_e32 v171, 0xffff0000, v149
	v_pk_add_f32 v[168:169], v[96:97], v[168:169]
	v_pk_add_f32 v[170:171], v[98:99], v[170:171]
	v_cvt_pk_bf16_f32 v148, v168, v169
	v_cvt_pk_bf16_f32 v149, v170, v171
	v_lshlrev_b32_e32 v168, 16, v150
	v_and_b32_e32 v169, 0xffff0000, v150
	v_lshlrev_b32_e32 v170, 16, v151
	v_and_b32_e32 v171, 0xffff0000, v151
	v_pk_add_f32 v[168:169], v[100:101], v[168:169]
	v_pk_add_f32 v[170:171], v[102:103], v[170:171]
	v_cvt_pk_bf16_f32 v150, v168, v169
	v_cvt_pk_bf16_f32 v151, v170, v171
	ds_write_b128 v67, v[148:151] offset:11296
	s_waitcnt vmcnt(3)
	v_lshlrev_b32_e32 v168, 16, v152
	v_and_b32_e32 v169, 0xffff0000, v152
	v_lshlrev_b32_e32 v170, 16, v153
	v_and_b32_e32 v171, 0xffff0000, v153
	v_pk_add_f32 v[168:169], v[72:73], v[168:169]
	v_pk_add_f32 v[170:171], v[74:75], v[170:171]
	v_cvt_pk_bf16_f32 v152, v168, v169
	v_cvt_pk_bf16_f32 v153, v170, v171
	v_lshlrev_b32_e32 v168, 16, v154
	v_and_b32_e32 v169, 0xffff0000, v154
	v_lshlrev_b32_e32 v170, 16, v155
	v_and_b32_e32 v171, 0xffff0000, v155
	v_pk_add_f32 v[168:169], v[76:77], v[168:169]
	v_pk_add_f32 v[170:171], v[78:79], v[170:171]
	v_cvt_pk_bf16_f32 v154, v168, v169
	v_cvt_pk_bf16_f32 v155, v170, v171
	ds_write_b128 v67, v[152:155] offset:12336
	s_waitcnt vmcnt(2)
	v_lshlrev_b32_e32 v168, 16, v156
	v_and_b32_e32 v169, 0xffff0000, v156
	v_lshlrev_b32_e32 v170, 16, v157
	v_and_b32_e32 v171, 0xffff0000, v157
	v_pk_add_f32 v[168:169], v[80:81], v[168:169]
	v_pk_add_f32 v[170:171], v[82:83], v[170:171]
	v_cvt_pk_bf16_f32 v156, v168, v169
	v_cvt_pk_bf16_f32 v157, v170, v171
	v_lshlrev_b32_e32 v168, 16, v158
	v_and_b32_e32 v169, 0xffff0000, v158
	v_lshlrev_b32_e32 v170, 16, v159
	v_and_b32_e32 v171, 0xffff0000, v159
	v_pk_add_f32 v[168:169], v[84:85], v[168:169]
	v_pk_add_f32 v[170:171], v[86:87], v[170:171]
	v_cvt_pk_bf16_f32 v158, v168, v169
	v_cvt_pk_bf16_f32 v159, v170, v171
	ds_write_b128 v67, v[156:159] offset:13360
	s_waitcnt vmcnt(1)
	v_lshlrev_b32_e32 v168, 16, v160
	v_and_b32_e32 v169, 0xffff0000, v160
	v_lshlrev_b32_e32 v170, 16, v161
	v_and_b32_e32 v171, 0xffff0000, v161
	v_pk_add_f32 v[168:169], v[88:89], v[168:169]
	v_pk_add_f32 v[170:171], v[90:91], v[170:171]
	v_cvt_pk_bf16_f32 v160, v168, v169
	v_cvt_pk_bf16_f32 v161, v170, v171
	v_lshlrev_b32_e32 v168, 16, v162
	v_and_b32_e32 v169, 0xffff0000, v162
	v_lshlrev_b32_e32 v170, 16, v163
	v_and_b32_e32 v171, 0xffff0000, v163
	v_pk_add_f32 v[168:169], v[92:93], v[168:169]
	v_pk_add_f32 v[170:171], v[94:95], v[170:171]
	v_cvt_pk_bf16_f32 v162, v168, v169
	v_cvt_pk_bf16_f32 v163, v170, v171
	ds_write_b128 v67, v[160:163] offset:14384
	s_waitcnt vmcnt(0)
	v_lshlrev_b32_e32 v168, 16, v164
	v_and_b32_e32 v169, 0xffff0000, v164
	v_lshlrev_b32_e32 v170, 16, v165
	v_and_b32_e32 v171, 0xffff0000, v165
	v_pk_add_f32 v[168:169], v[96:97], v[168:169]
	v_pk_add_f32 v[170:171], v[98:99], v[170:171]
	v_cvt_pk_bf16_f32 v164, v168, v169
	v_cvt_pk_bf16_f32 v165, v170, v171
	v_lshlrev_b32_e32 v168, 16, v166
	v_and_b32_e32 v169, 0xffff0000, v166
	v_lshlrev_b32_e32 v170, 16, v167
	v_and_b32_e32 v171, 0xffff0000, v167
	v_pk_add_f32 v[168:169], v[100:101], v[168:169]
	v_pk_add_f32 v[170:171], v[102:103], v[170:171]
	v_cvt_pk_bf16_f32 v166, v168, v169
	v_cvt_pk_bf16_f32 v167, v170, v171
	ds_write_b128 v67, v[164:167] offset:15408
	v_lshl_add_u64 v[70:71], v[38:39], 0, v[0:1]
	v_mul_u32_u24_e32 v69, 0x1010, v41
	v_add_u32_e32 v69, v69, v0
	v_add_u32_e32 v69, 0x7000, v69
	global_load_dwordx4 v[72:75], v[70:71], off offset:-128
	global_load_dwordx4 v[76:79], v[70:71], off offset:-96
	global_load_dwordx4 v[80:83], v[70:71], off offset:-64
	global_load_dwordx4 v[84:87], v[70:71], off offset:-32
	global_load_dwordx4 v[88:91], v[70:71], off
	global_load_dwordx4 v[92:95], v[70:71], off offset:32
	global_load_dwordx4 v[96:99], v[70:71], off offset:64
	global_load_dwordx4 v[100:103], v[70:71], off offset:96
	global_load_dwordx4 v[168:171], v[70:71], off offset:128
	global_load_dwordx4 v[172:175], v[70:71], off offset:160
	global_load_dwordx4 v[176:179], v[70:71], off offset:192
	global_load_dwordx4 v[180:183], v[70:71], off offset:224
	global_load_dwordx4 v[184:187], v[70:71], off offset:256
	global_load_dwordx4 v[188:191], v[70:71], off offset:288
	global_load_dwordx4 v[192:195], v[70:71], off offset:320
	global_load_dwordx4 v[196:199], v[70:71], off offset:352
	s_waitcnt lgkmcnt(0)
	s_barrier
; #define LAS __attribute__((address_space(3)))
; __device__ __forceinline__ v16f mfma32(v8s a, v8s b, v16f c) { return __builtin_amdgcn_mfma_f32_32x32x16_bf16(a, b, c, 0, 0, 0); }
; __device__ __forceinline__ void compress_unit(LAS unsigned char* lds, int u, const bf16_t* QKV, const float* pe_k, const float* pe_v,
;                                               const bf16_t* CW1  , const bf16_t* CW2  , bf16_t* KCMP, bf16_t* VCMP) {
;     ...
;     for (int st = 0; st < 128; ++st) {
;         const int li = st >> 2, d0 = (st & 3) * 16;
;         const v4u ar = *(const v4u*)(Ag + (size_t)li * EVEN_PAD + d0);
;         const v4f pa = *(const LAS v4f*)(PE + li * 64 + d0 + hi * 8), pb = *(const LAS v4f*)(PE + li * 64 + d0 + hi * 8 + 4);
;         const v8s bfr = *(const v8s*)(Bg + st * 16);
;         v4u aw;
;         aw.x = pkbf(__uint_as_float(ar.x << 16) + pa.x, __uint_as_float(ar.x & 0xffff0000u) + pa.y);
;         aw.y = pkbf(__uint_as_float(ar.y << 16) + pa.z, __uint_as_float(ar.y & 0xffff0000u) + pa.w);
;         aw.z = pkbf(__uint_as_float(ar.z << 16) + pb.x, __uint_as_float(ar.z & 0xffff0000u) + pb.y);
;         aw.w = pkbf(__uint_as_float(ar.w << 16) + pb.z, __uint_as_float(ar.w & 0xffff0000u) + pb.w);
;         acc = mfma32(__builtin_bit_cast(v8s, aw), bfr, acc);
;     }
	ds_read_b128 v[104:107], v69
	ds_read_b128 v[108:111], v69 offset:32
	ds_read_b128 v[112:115], v69 offset:64
	ds_read_b128 v[116:119], v69 offset:96
	ds_read_b128 v[120:123], v69 offset:128
	ds_read_b128 v[124:127], v69 offset:160
	ds_read_b128 v[128:131], v69 offset:192
	ds_read_b128 v[132:135], v69 offset:224
	ds_read_b128 v[136:139], v69 offset:256
	ds_read_b128 v[140:143], v69 offset:288
	ds_read_b128 v[144:147], v69 offset:320
	ds_read_b128 v[148:151], v69 offset:352
	ds_read_b128 v[152:155], v69 offset:384
	ds_read_b128 v[156:159], v69 offset:416
	ds_read_b128 v[160:163], v69 offset:448
	ds_read_b128 v[164:167], v69 offset:480
	s_waitcnt lgkmcnt(8)
	s_waitcnt vmcnt(15)
	v_mfma_f32_32x32x16_bf16 v[2:17], v[104:107], v[72:75], v[2:17]
	global_load_dwordx4 v[72:75], v[70:71], off offset:384
	s_waitcnt vmcnt(15)
	v_mfma_f32_32x32x16_bf16 v[2:17], v[108:111], v[76:79], v[2:17]
	global_load_dwordx4 v[76:79], v[70:71], off offset:416
	s_waitcnt vmcnt(15)
	v_mfma_f32_32x32x16_bf16 v[2:17], v[112:115], v[80:83], v[2:17]
	global_load_dwordx4 v[80:83], v[70:71], off offset:448
	s_waitcnt vmcnt(15)
	v_mfma_f32_32x32x16_bf16 v[2:17], v[116:119], v[84:87], v[2:17]
	global_load_dwordx4 v[84:87], v[70:71], off offset:480
	s_waitcnt vmcnt(15)
	v_mfma_f32_32x32x16_bf16 v[2:17], v[120:123], v[88:91], v[2:17]
	global_load_dwordx4 v[88:91], v[70:71], off offset:512
	s_waitcnt vmcnt(15)
	v_mfma_f32_32x32x16_bf16 v[2:17], v[124:127], v[92:95], v[2:17]
	global_load_dwordx4 v[92:95], v[70:71], off offset:544
	s_waitcnt vmcnt(15)
	v_mfma_f32_32x32x16_bf16 v[2:17], v[128:131], v[96:99], v[2:17]
	global_load_dwordx4 v[96:99], v[70:71], off offset:576
	s_waitcnt vmcnt(15)
	v_mfma_f32_32x32x16_bf16 v[2:17], v[132:135], v[100:103], v[2:17]
	global_load_dwordx4 v[100:103], v[70:71], off offset:608
	ds_read_b128 v[104:107], v69 offset:512
	ds_read_b128 v[108:111], v69 offset:544
	ds_read_b128 v[112:115], v69 offset:576
	ds_read_b128 v[116:119], v69 offset:608
	ds_read_b128 v[120:123], v69 offset:640
	ds_read_b128 v[124:127], v69 offset:672
	ds_read_b128 v[128:131], v69 offset:704
	ds_read_b128 v[132:135], v69 offset:736
	s_waitcnt lgkmcnt(8)
	s_waitcnt vmcnt(15)
	v_mfma_f32_32x32x16_bf16 v[2:17], v[136:139], v[168:171], v[2:17]
	global_load_dwordx4 v[168:171], v[70:71], off offset:640
	s_waitcnt vmcnt(15)
	v_mfma_f32_32x32x16_bf16 v[2:17], v[140:143], v[172:175], v[2:17]
	global_load_dwordx4 v[172:175], v[70:71], off offset:672
	s_waitcnt vmcnt(15)
	v_mfma_f32_32x32x16_bf16 v[2:17], v[144:147], v[176:179], v[2:17]
	global_load_dwordx4 v[176:179], v[70:71], off offset:704
	s_waitcnt vmcnt(15)
	v_mfma_f32_32x32x16_bf16 v[2:17], v[148:151], v[180:183], v[2:17]
	global_load_dwordx4 v[180:183], v[70:71], off offset:736
	s_waitcnt vmcnt(15)
	v_mfma_f32_32x32x16_bf16 v[2:17], v[152:155], v[184:187], v[2:17]
	global_load_dwordx4 v[184:187], v[70:71], off offset:768
	s_waitcnt vmcnt(15)
	v_mfma_f32_32x32x16_bf16 v[2:17], v[156:159], v[188:191], v[2:17]
	global_load_dwordx4 v[188:191], v[70:71], off offset:800
	s_waitcnt vmcnt(15)
	v_mfma_f32_32x32x16_bf16 v[2:17], v[160:163], v[192:195], v[2:17]
	global_load_dwordx4 v[192:195], v[70:71], off offset:832
	s_waitcnt vmcnt(15)
	v_mfma_f32_32x32x16_bf16 v[2:17], v[164:167], v[196:199], v[2:17]
	global_load_dwordx4 v[196:199], v[70:71], off offset:864
	ds_read_b128 v[136:139], v69 offset:768
	ds_read_b128 v[140:143], v69 offset:800
	ds_read_b128 v[144:147], v69 offset:832
	ds_read_b128 v[148:151], v69 offset:864
	ds_read_b128 v[152:155], v69 offset:896
	ds_read_b128 v[156:159], v69 offset:928
	ds_read_b128 v[160:163], v69 offset:960
	ds_read_b128 v[164:167], v69 offset:992
	s_waitcnt lgkmcnt(8)
	s_waitcnt vmcnt(15)
	v_mfma_f32_32x32x16_bf16 v[2:17], v[104:107], v[72:75], v[2:17]
	global_load_dwordx4 v[72:75], v[70:71], off offset:896
	s_waitcnt vmcnt(15)
	v_mfma_f32_32x32x16_bf16 v[2:17], v[108:111], v[76:79], v[2:17]
	global_load_dwordx4 v[76:79], v[70:71], off offset:928
	s_waitcnt vmcnt(15)
	v_mfma_f32_32x32x16_bf16 v[2:17], v[112:115], v[80:83], v[2:17]
	global_load_dwordx4 v[80:83], v[70:71], off offset:960
	s_waitcnt vmcnt(15)
	v_mfma_f32_32x32x16_bf16 v[2:17], v[116:119], v[84:87], v[2:17]
	global_load_dwordx4 v[84:87], v[70:71], off offset:992
	s_waitcnt vmcnt(15)
	v_mfma_f32_32x32x16_bf16 v[2:17], v[120:123], v[88:91], v[2:17]
	global_load_dwordx4 v[88:91], v[70:71], off offset:1024
	s_waitcnt vmcnt(15)
	v_mfma_f32_32x32x16_bf16 v[2:17], v[124:127], v[92:95], v[2:17]
	global_load_dwordx4 v[92:95], v[70:71], off offset:1056
	s_waitcnt vmcnt(15)
	v_mfma_f32_32x32x16_bf16 v[2:17], v[128:131], v[96:99], v[2:17]
	global_load_dwordx4 v[96:99], v[70:71], off offset:1088
	s_waitcnt vmcnt(15)
	v_mfma_f32_32x32x16_bf16 v[2:17], v[132:135], v[100:103], v[2:17]
	global_load_dwordx4 v[100:103], v[70:71], off offset:1120
	ds_read_b128 v[104:107], v69 offset:1024
	ds_read_b128 v[108:111], v69 offset:1056
	ds_read_b128 v[112:115], v69 offset:1088
	ds_read_b128 v[116:119], v69 offset:1120
	ds_read_b128 v[120:123], v69 offset:1152
	ds_read_b128 v[124:127], v69 offset:1184
	ds_read_b128 v[128:131], v69 offset:1216
	ds_read_b128 v[132:135], v69 offset:1248
	s_waitcnt lgkmcnt(8)
	s_waitcnt vmcnt(15)
	v_mfma_f32_32x32x16_bf16 v[2:17], v[136:139], v[168:171], v[2:17]
	global_load_dwordx4 v[168:171], v[70:71], off offset:1152
	s_waitcnt vmcnt(15)
	v_mfma_f32_32x32x16_bf16 v[2:17], v[140:143], v[172:175], v[2:17]
	global_load_dwordx4 v[172:175], v[70:71], off offset:1184
	s_waitcnt vmcnt(15)
	v_mfma_f32_32x32x16_bf16 v[2:17], v[144:147], v[176:179], v[2:17]
	global_load_dwordx4 v[176:179], v[70:71], off offset:1216
	s_waitcnt vmcnt(15)
; #define LAS __attribute__((address_space(3)))
; __device__ __forceinline__ v16f mfma32(v8s a, v8s b, v16f c) { return __builtin_amdgcn_mfma_f32_32x32x16_bf16(a, b, c, 0, 0, 0); }
; __device__ __forceinline__ void compress_unit(LAS unsigned char* lds, int u, const bf16_t* QKV, const float* pe_k, const float* pe_v,
;                                               const bf16_t* CW1  , const bf16_t* CW2  , bf16_t* KCMP, bf16_t* VCMP) {
;     ...
;     for (int st = 0; st < 128; ++st) {
;         const int li = st >> 2, d0 = (st & 3) * 16;
;         const v4u ar = *(const v4u*)(Ag + (size_t)li * EVEN_PAD + d0);
;         const v4f pa = *(const LAS v4f*)(PE + li * 64 + d0 + hi * 8), pb = *(const LAS v4f*)(PE + li * 64 + d0 + hi * 8 + 4);
;         const v8s bfr = *(const v8s*)(Bg + st * 16);
;         v4u aw;
;         aw.x = pkbf(__uint_as_float(ar.x << 16) + pa.x, __uint_as_float(ar.x & 0xffff0000u) + pa.y);
;         aw.y = pkbf(__uint_as_float(ar.y << 16) + pa.z, __uint_as_float(ar.y & 0xffff0000u) + pa.w);
;         aw.z = pkbf(__uint_as_float(ar.z << 16) + pb.x, __uint_as_float(ar.z & 0xffff0000u) + pb.y);
;         aw.w = pkbf(__uint_as_float(ar.w << 16) + pb.z, __uint_as_float(ar.w & 0xffff0000u) + pb.w);
;         acc = mfma32(__builtin_bit_cast(v8s, aw), bfr, acc);
;     }
	v_mfma_f32_32x32x16_bf16 v[2:17], v[148:151], v[180:183], v[2:17]
	global_load_dwordx4 v[180:183], v[70:71], off offset:1248
	s_waitcnt vmcnt(15)
	v_mfma_f32_32x32x16_bf16 v[2:17], v[152:155], v[184:187], v[2:17]
	global_load_dwordx4 v[184:187], v[70:71], off offset:1280
	s_waitcnt vmcnt(15)
	v_mfma_f32_32x32x16_bf16 v[2:17], v[156:159], v[188:191], v[2:17]
	global_load_dwordx4 v[188:191], v[70:71], off offset:1312
	s_waitcnt vmcnt(15)
	v_mfma_f32_32x32x16_bf16 v[2:17], v[160:163], v[192:195], v[2:17]
	global_load_dwordx4 v[192:195], v[70:71], off offset:1344
	s_waitcnt vmcnt(15)
	v_mfma_f32_32x32x16_bf16 v[2:17], v[164:167], v[196:199], v[2:17]
	global_load_dwordx4 v[196:199], v[70:71], off offset:1376
	ds_read_b128 v[136:139], v69 offset:1280
	ds_read_b128 v[140:143], v69 offset:1312
	ds_read_b128 v[144:147], v69 offset:1344
	ds_read_b128 v[148:151], v69 offset:1376
	ds_read_b128 v[152:155], v69 offset:1408
	ds_read_b128 v[156:159], v69 offset:1440
	ds_read_b128 v[160:163], v69 offset:1472
	ds_read_b128 v[164:167], v69 offset:1504
	s_waitcnt lgkmcnt(8)
	s_waitcnt vmcnt(15)
	v_mfma_f32_32x32x16_bf16 v[2:17], v[104:107], v[72:75], v[2:17]
	global_load_dwordx4 v[72:75], v[70:71], off offset:1408
	s_waitcnt vmcnt(15)
	v_mfma_f32_32x32x16_bf16 v[2:17], v[108:111], v[76:79], v[2:17]
	global_load_dwordx4 v[76:79], v[70:71], off offset:1440
	s_waitcnt vmcnt(15)
	v_mfma_f32_32x32x16_bf16 v[2:17], v[112:115], v[80:83], v[2:17]
	global_load_dwordx4 v[80:83], v[70:71], off offset:1472
	s_waitcnt vmcnt(15)
	v_mfma_f32_32x32x16_bf16 v[2:17], v[116:119], v[84:87], v[2:17]
	global_load_dwordx4 v[84:87], v[70:71], off offset:1504
	s_waitcnt vmcnt(15)
	v_mfma_f32_32x32x16_bf16 v[2:17], v[120:123], v[88:91], v[2:17]
	global_load_dwordx4 v[88:91], v[70:71], off offset:1536
	s_waitcnt vmcnt(15)
	v_mfma_f32_32x32x16_bf16 v[2:17], v[124:127], v[92:95], v[2:17]
	global_load_dwordx4 v[92:95], v[70:71], off offset:1568
	s_waitcnt vmcnt(15)
	v_mfma_f32_32x32x16_bf16 v[2:17], v[128:131], v[96:99], v[2:17]
	global_load_dwordx4 v[96:99], v[70:71], off offset:1600
	s_waitcnt vmcnt(15)
	v_mfma_f32_32x32x16_bf16 v[2:17], v[132:135], v[100:103], v[2:17]
	global_load_dwordx4 v[100:103], v[70:71], off offset:1632
	ds_read_b128 v[104:107], v69 offset:1536
	ds_read_b128 v[108:111], v69 offset:1568
	ds_read_b128 v[112:115], v69 offset:1600
	ds_read_b128 v[116:119], v69 offset:1632
	ds_read_b128 v[120:123], v69 offset:1664
	ds_read_b128 v[124:127], v69 offset:1696
	ds_read_b128 v[128:131], v69 offset:1728
	ds_read_b128 v[132:135], v69 offset:1760
	s_waitcnt lgkmcnt(8)
	s_waitcnt vmcnt(15)
	v_mfma_f32_32x32x16_bf16 v[2:17], v[136:139], v[168:171], v[2:17]
	global_load_dwordx4 v[168:171], v[70:71], off offset:1664
	s_waitcnt vmcnt(15)
	v_mfma_f32_32x32x16_bf16 v[2:17], v[140:143], v[172:175], v[2:17]
	global_load_dwordx4 v[172:175], v[70:71], off offset:1696
	s_waitcnt vmcnt(15)
	v_mfma_f32_32x32x16_bf16 v[2:17], v[144:147], v[176:179], v[2:17]
	global_load_dwordx4 v[176:179], v[70:71], off offset:1728
	s_waitcnt vmcnt(15)
	v_mfma_f32_32x32x16_bf16 v[2:17], v[148:151], v[180:183], v[2:17]
	global_load_dwordx4 v[180:183], v[70:71], off offset:1760
	s_waitcnt vmcnt(15)
	v_mfma_f32_32x32x16_bf16 v[2:17], v[152:155], v[184:187], v[2:17]
	global_load_dwordx4 v[184:187], v[70:71], off offset:1792
	s_waitcnt vmcnt(15)
	v_mfma_f32_32x32x16_bf16 v[2:17], v[156:159], v[188:191], v[2:17]
	global_load_dwordx4 v[188:191], v[70:71], off offset:1824
	s_waitcnt vmcnt(15)
	v_mfma_f32_32x32x16_bf16 v[2:17], v[160:163], v[192:195], v[2:17]
	global_load_dwordx4 v[192:195], v[70:71], off offset:1856
	s_waitcnt vmcnt(15)
	v_mfma_f32_32x32x16_bf16 v[2:17], v[164:167], v[196:199], v[2:17]
	global_load_dwordx4 v[196:199], v[70:71], off offset:1888
	ds_read_b128 v[136:139], v69 offset:1792
	ds_read_b128 v[140:143], v69 offset:1824
	ds_read_b128 v[144:147], v69 offset:1856
	ds_read_b128 v[148:151], v69 offset:1888
	ds_read_b128 v[152:155], v69 offset:1920
	ds_read_b128 v[156:159], v69 offset:1952
	ds_read_b128 v[160:163], v69 offset:1984
	ds_read_b128 v[164:167], v69 offset:2016
	s_waitcnt lgkmcnt(8)
	s_waitcnt vmcnt(15)
	v_mfma_f32_32x32x16_bf16 v[2:17], v[104:107], v[72:75], v[2:17]
	global_load_dwordx4 v[72:75], v[70:71], off offset:1920
	s_waitcnt vmcnt(15)
	v_mfma_f32_32x32x16_bf16 v[2:17], v[108:111], v[76:79], v[2:17]
	global_load_dwordx4 v[76:79], v[70:71], off offset:1952
	s_waitcnt vmcnt(15)
	v_mfma_f32_32x32x16_bf16 v[2:17], v[112:115], v[80:83], v[2:17]
	global_load_dwordx4 v[80:83], v[70:71], off offset:1984
	s_waitcnt vmcnt(15)
	v_mfma_f32_32x32x16_bf16 v[2:17], v[116:119], v[84:87], v[2:17]
	global_load_dwordx4 v[84:87], v[70:71], off offset:2016
	s_waitcnt vmcnt(15)
	v_mfma_f32_32x32x16_bf16 v[2:17], v[120:123], v[88:91], v[2:17]
	global_load_dwordx4 v[88:91], v[70:71], off offset:2048
	s_waitcnt vmcnt(15)
	v_mfma_f32_32x32x16_bf16 v[2:17], v[124:127], v[92:95], v[2:17]
	global_load_dwordx4 v[92:95], v[70:71], off offset:2080
	s_waitcnt vmcnt(15)
	v_mfma_f32_32x32x16_bf16 v[2:17], v[128:131], v[96:99], v[2:17]
	global_load_dwordx4 v[96:99], v[70:71], off offset:2112
	s_waitcnt vmcnt(15)
	v_mfma_f32_32x32x16_bf16 v[2:17], v[132:135], v[100:103], v[2:17]
	global_load_dwordx4 v[100:103], v[70:71], off offset:2144
	ds_read_b128 v[104:107], v69 offset:2048
	ds_read_b128 v[108:111], v69 offset:2080
	ds_read_b128 v[112:115], v69 offset:2112
	ds_read_b128 v[116:119], v69 offset:2144
	ds_read_b128 v[120:123], v69 offset:2176
	ds_read_b128 v[124:127], v69 offset:2208
	ds_read_b128 v[128:131], v69 offset:2240
	ds_read_b128 v[132:135], v69 offset:2272
	s_waitcnt lgkmcnt(8)
	s_waitcnt vmcnt(15)
; #define LAS __attribute__((address_space(3)))
; __device__ __forceinline__ v16f mfma32(v8s a, v8s b, v16f c) { return __builtin_amdgcn_mfma_f32_32x32x16_bf16(a, b, c, 0, 0, 0); }
; __device__ __forceinline__ void compress_unit(LAS unsigned char* lds, int u, const bf16_t* QKV, const float* pe_k, const float* pe_v,
;                                               const bf16_t* CW1  , const bf16_t* CW2  , bf16_t* KCMP, bf16_t* VCMP) {
;     ...
;     for (int st = 0; st < 128; ++st) {
;         const int li = st >> 2, d0 = (st & 3) * 16;
;         const v4u ar = *(const v4u*)(Ag + (size_t)li * EVEN_PAD + d0);
;         const v4f pa = *(const LAS v4f*)(PE + li * 64 + d0 + hi * 8), pb = *(const LAS v4f*)(PE + li * 64 + d0 + hi * 8 + 4);
;         const v8s bfr = *(const v8s*)(Bg + st * 16);
;         v4u aw;
;         aw.x = pkbf(__uint_as_float(ar.x << 16) + pa.x, __uint_as_float(ar.x & 0xffff0000u) + pa.y);
;         aw.y = pkbf(__uint_as_float(ar.y << 16) + pa.z, __uint_as_float(ar.y & 0xffff0000u) + pa.w);
;         aw.z = pkbf(__uint_as_float(ar.z << 16) + pb.x, __uint_as_float(ar.z & 0xffff0000u) + pb.y);
;         aw.w = pkbf(__uint_as_float(ar.w << 16) + pb.z, __uint_as_float(ar.w & 0xffff0000u) + pb.w);
;         acc = mfma32(__builtin_bit_cast(v8s, aw), bfr, acc);
;     }
	v_mfma_f32_32x32x16_bf16 v[2:17], v[136:139], v[168:171], v[2:17]
	global_load_dwordx4 v[168:171], v[70:71], off offset:2176
	s_waitcnt vmcnt(15)
	v_mfma_f32_32x32x16_bf16 v[2:17], v[140:143], v[172:175], v[2:17]
	global_load_dwordx4 v[172:175], v[70:71], off offset:2208
	s_waitcnt vmcnt(15)
	v_mfma_f32_32x32x16_bf16 v[2:17], v[144:147], v[176:179], v[2:17]
	global_load_dwordx4 v[176:179], v[70:71], off offset:2240
	s_waitcnt vmcnt(15)
	v_mfma_f32_32x32x16_bf16 v[2:17], v[148:151], v[180:183], v[2:17]
	global_load_dwordx4 v[180:183], v[70:71], off offset:2272
	s_waitcnt vmcnt(15)
	v_mfma_f32_32x32x16_bf16 v[2:17], v[152:155], v[184:187], v[2:17]
	global_load_dwordx4 v[184:187], v[70:71], off offset:2304
	s_waitcnt vmcnt(15)
	v_mfma_f32_32x32x16_bf16 v[2:17], v[156:159], v[188:191], v[2:17]
	global_load_dwordx4 v[188:191], v[70:71], off offset:2336
	s_waitcnt vmcnt(15)
	v_mfma_f32_32x32x16_bf16 v[2:17], v[160:163], v[192:195], v[2:17]
	global_load_dwordx4 v[192:195], v[70:71], off offset:2368
	s_waitcnt vmcnt(15)
	v_mfma_f32_32x32x16_bf16 v[2:17], v[164:167], v[196:199], v[2:17]
	global_load_dwordx4 v[196:199], v[70:71], off offset:2400
	ds_read_b128 v[136:139], v69 offset:2304
	ds_read_b128 v[140:143], v69 offset:2336
	ds_read_b128 v[144:147], v69 offset:2368
	ds_read_b128 v[148:151], v69 offset:2400
	ds_read_b128 v[152:155], v69 offset:2432
	ds_read_b128 v[156:159], v69 offset:2464
	ds_read_b128 v[160:163], v69 offset:2496
	ds_read_b128 v[164:167], v69 offset:2528
	s_waitcnt lgkmcnt(8)
	s_waitcnt vmcnt(15)
	v_mfma_f32_32x32x16_bf16 v[2:17], v[104:107], v[72:75], v[2:17]
	global_load_dwordx4 v[72:75], v[70:71], off offset:2432
	s_waitcnt vmcnt(15)
	v_mfma_f32_32x32x16_bf16 v[2:17], v[108:111], v[76:79], v[2:17]
	global_load_dwordx4 v[76:79], v[70:71], off offset:2464
	s_waitcnt vmcnt(15)
	v_mfma_f32_32x32x16_bf16 v[2:17], v[112:115], v[80:83], v[2:17]
	global_load_dwordx4 v[80:83], v[70:71], off offset:2496
	s_waitcnt vmcnt(15)
	v_mfma_f32_32x32x16_bf16 v[2:17], v[116:119], v[84:87], v[2:17]
	global_load_dwordx4 v[84:87], v[70:71], off offset:2528
	s_waitcnt vmcnt(15)
	v_mfma_f32_32x32x16_bf16 v[2:17], v[120:123], v[88:91], v[2:17]
	global_load_dwordx4 v[88:91], v[70:71], off offset:2560
	s_waitcnt vmcnt(15)
	v_mfma_f32_32x32x16_bf16 v[2:17], v[124:127], v[92:95], v[2:17]
	global_load_dwordx4 v[92:95], v[70:71], off offset:2592
	s_waitcnt vmcnt(15)
	v_mfma_f32_32x32x16_bf16 v[2:17], v[128:131], v[96:99], v[2:17]
	global_load_dwordx4 v[96:99], v[70:71], off offset:2624
	s_waitcnt vmcnt(15)
	v_mfma_f32_32x32x16_bf16 v[2:17], v[132:135], v[100:103], v[2:17]
	global_load_dwordx4 v[100:103], v[70:71], off offset:2656
	ds_read_b128 v[104:107], v69 offset:2560
	ds_read_b128 v[108:111], v69 offset:2592
	ds_read_b128 v[112:115], v69 offset:2624
	ds_read_b128 v[116:119], v69 offset:2656
	ds_read_b128 v[120:123], v69 offset:2688
	ds_read_b128 v[124:127], v69 offset:2720
	ds_read_b128 v[128:131], v69 offset:2752
	ds_read_b128 v[132:135], v69 offset:2784
	s_waitcnt lgkmcnt(8)
	s_waitcnt vmcnt(15)
	v_mfma_f32_32x32x16_bf16 v[2:17], v[136:139], v[168:171], v[2:17]
	global_load_dwordx4 v[168:171], v[70:71], off offset:2688
	s_waitcnt vmcnt(15)
	v_mfma_f32_32x32x16_bf16 v[2:17], v[140:143], v[172:175], v[2:17]
	global_load_dwordx4 v[172:175], v[70:71], off offset:2720
	s_waitcnt vmcnt(15)
	v_mfma_f32_32x32x16_bf16 v[2:17], v[144:147], v[176:179], v[2:17]
	global_load_dwordx4 v[176:179], v[70:71], off offset:2752
	s_waitcnt vmcnt(15)
	v_mfma_f32_32x32x16_bf16 v[2:17], v[148:151], v[180:183], v[2:17]
	global_load_dwordx4 v[180:183], v[70:71], off offset:2784
	s_waitcnt vmcnt(15)
	v_mfma_f32_32x32x16_bf16 v[2:17], v[152:155], v[184:187], v[2:17]
	global_load_dwordx4 v[184:187], v[70:71], off offset:2816
	s_waitcnt vmcnt(15)
	v_mfma_f32_32x32x16_bf16 v[2:17], v[156:159], v[188:191], v[2:17]
	global_load_dwordx4 v[188:191], v[70:71], off offset:2848
	s_waitcnt vmcnt(15)
	v_mfma_f32_32x32x16_bf16 v[2:17], v[160:163], v[192:195], v[2:17]
	global_load_dwordx4 v[192:195], v[70:71], off offset:2880
	s_waitcnt vmcnt(15)
	v_mfma_f32_32x32x16_bf16 v[2:17], v[164:167], v[196:199], v[2:17]
	global_load_dwordx4 v[196:199], v[70:71], off offset:2912
	ds_read_b128 v[136:139], v69 offset:2816
	ds_read_b128 v[140:143], v69 offset:2848
	ds_read_b128 v[144:147], v69 offset:2880
	ds_read_b128 v[148:151], v69 offset:2912
	ds_read_b128 v[152:155], v69 offset:2944
	ds_read_b128 v[156:159], v69 offset:2976
	ds_read_b128 v[160:163], v69 offset:3008
	ds_read_b128 v[164:167], v69 offset:3040
	s_waitcnt lgkmcnt(8)
	s_waitcnt vmcnt(15)
	v_mfma_f32_32x32x16_bf16 v[2:17], v[104:107], v[72:75], v[2:17]
	global_load_dwordx4 v[72:75], v[70:71], off offset:2944
	s_waitcnt vmcnt(15)
	v_mfma_f32_32x32x16_bf16 v[2:17], v[108:111], v[76:79], v[2:17]
	global_load_dwordx4 v[76:79], v[70:71], off offset:2976
	s_waitcnt vmcnt(15)
	v_mfma_f32_32x32x16_bf16 v[2:17], v[112:115], v[80:83], v[2:17]
	global_load_dwordx4 v[80:83], v[70:71], off offset:3008
	s_waitcnt vmcnt(15)
	v_mfma_f32_32x32x16_bf16 v[2:17], v[116:119], v[84:87], v[2:17]
	global_load_dwordx4 v[84:87], v[70:71], off offset:3040
	s_waitcnt vmcnt(15)
	v_mfma_f32_32x32x16_bf16 v[2:17], v[120:123], v[88:91], v[2:17]
	global_load_dwordx4 v[88:91], v[70:71], off offset:3072
	s_waitcnt vmcnt(15)
	v_mfma_f32_32x32x16_bf16 v[2:17], v[124:127], v[92:95], v[2:17]
	global_load_dwordx4 v[92:95], v[70:71], off offset:3104
	s_waitcnt vmcnt(15)
	v_mfma_f32_32x32x16_bf16 v[2:17], v[128:131], v[96:99], v[2:17]
	global_load_dwordx4 v[96:99], v[70:71], off offset:3136
	s_waitcnt vmcnt(15)
; #define LAS __attribute__((address_space(3)))
; __device__ __forceinline__ v16f mfma32(v8s a, v8s b, v16f c) { return __builtin_amdgcn_mfma_f32_32x32x16_bf16(a, b, c, 0, 0, 0); }
; __device__ __forceinline__ void compress_unit(LAS unsigned char* lds, int u, const bf16_t* QKV, const float* pe_k, const float* pe_v,
;                                               const bf16_t* CW1  , const bf16_t* CW2  , bf16_t* KCMP, bf16_t* VCMP) {
;     ...
;     for (int st = 0; st < 128; ++st) {
;         const int li = st >> 2, d0 = (st & 3) * 16;
;         const v4u ar = *(const v4u*)(Ag + (size_t)li * EVEN_PAD + d0);
;         const v4f pa = *(const LAS v4f*)(PE + li * 64 + d0 + hi * 8), pb = *(const LAS v4f*)(PE + li * 64 + d0 + hi * 8 + 4);
;         const v8s bfr = *(const v8s*)(Bg + st * 16);
;         v4u aw;
;         aw.x = pkbf(__uint_as_float(ar.x << 16) + pa.x, __uint_as_float(ar.x & 0xffff0000u) + pa.y);
;         aw.y = pkbf(__uint_as_float(ar.y << 16) + pa.z, __uint_as_float(ar.y & 0xffff0000u) + pa.w);
;         aw.z = pkbf(__uint_as_float(ar.z << 16) + pb.x, __uint_as_float(ar.z & 0xffff0000u) + pb.y);
;         aw.w = pkbf(__uint_as_float(ar.w << 16) + pb.z, __uint_as_float(ar.w & 0xffff0000u) + pb.w);
;         acc = mfma32(__builtin_bit_cast(v8s, aw), bfr, acc);
;     }
	v_mfma_f32_32x32x16_bf16 v[2:17], v[132:135], v[100:103], v[2:17]
	global_load_dwordx4 v[100:103], v[70:71], off offset:3168
	ds_read_b128 v[104:107], v69 offset:3072
	ds_read_b128 v[108:111], v69 offset:3104
	ds_read_b128 v[112:115], v69 offset:3136
	ds_read_b128 v[116:119], v69 offset:3168
	ds_read_b128 v[120:123], v69 offset:3200
	ds_read_b128 v[124:127], v69 offset:3232
	ds_read_b128 v[128:131], v69 offset:3264
	ds_read_b128 v[132:135], v69 offset:3296
	s_waitcnt lgkmcnt(8)
	s_waitcnt vmcnt(15)
	v_mfma_f32_32x32x16_bf16 v[2:17], v[136:139], v[168:171], v[2:17]
	global_load_dwordx4 v[168:171], v[70:71], off offset:3200
	s_waitcnt vmcnt(15)
	v_mfma_f32_32x32x16_bf16 v[2:17], v[140:143], v[172:175], v[2:17]
	global_load_dwordx4 v[172:175], v[70:71], off offset:3232
	s_waitcnt vmcnt(15)
	v_mfma_f32_32x32x16_bf16 v[2:17], v[144:147], v[176:179], v[2:17]
	global_load_dwordx4 v[176:179], v[70:71], off offset:3264
	s_waitcnt vmcnt(15)
	v_mfma_f32_32x32x16_bf16 v[2:17], v[148:151], v[180:183], v[2:17]
	global_load_dwordx4 v[180:183], v[70:71], off offset:3296
	s_waitcnt vmcnt(15)
	v_mfma_f32_32x32x16_bf16 v[2:17], v[152:155], v[184:187], v[2:17]
	global_load_dwordx4 v[184:187], v[70:71], off offset:3328
	s_waitcnt vmcnt(15)
	v_mfma_f32_32x32x16_bf16 v[2:17], v[156:159], v[188:191], v[2:17]
	global_load_dwordx4 v[188:191], v[70:71], off offset:3360
	s_waitcnt vmcnt(15)
	v_mfma_f32_32x32x16_bf16 v[2:17], v[160:163], v[192:195], v[2:17]
	global_load_dwordx4 v[192:195], v[70:71], off offset:3392
	s_waitcnt vmcnt(15)
	v_mfma_f32_32x32x16_bf16 v[2:17], v[164:167], v[196:199], v[2:17]
	global_load_dwordx4 v[196:199], v[70:71], off offset:3424
	ds_read_b128 v[136:139], v69 offset:3328
	ds_read_b128 v[140:143], v69 offset:3360
	ds_read_b128 v[144:147], v69 offset:3392
	ds_read_b128 v[148:151], v69 offset:3424
	ds_read_b128 v[152:155], v69 offset:3456
	ds_read_b128 v[156:159], v69 offset:3488
	ds_read_b128 v[160:163], v69 offset:3520
	ds_read_b128 v[164:167], v69 offset:3552
	s_waitcnt lgkmcnt(8)
	s_waitcnt vmcnt(15)
	v_mfma_f32_32x32x16_bf16 v[2:17], v[104:107], v[72:75], v[2:17]
	global_load_dwordx4 v[72:75], v[70:71], off offset:3456
	s_waitcnt vmcnt(15)
	v_mfma_f32_32x32x16_bf16 v[2:17], v[108:111], v[76:79], v[2:17]
	global_load_dwordx4 v[76:79], v[70:71], off offset:3488
	s_waitcnt vmcnt(15)
	v_mfma_f32_32x32x16_bf16 v[2:17], v[112:115], v[80:83], v[2:17]
	global_load_dwordx4 v[80:83], v[70:71], off offset:3520
	s_waitcnt vmcnt(15)
	v_mfma_f32_32x32x16_bf16 v[2:17], v[116:119], v[84:87], v[2:17]
	global_load_dwordx4 v[84:87], v[70:71], off offset:3552
	s_waitcnt vmcnt(15)
	v_mfma_f32_32x32x16_bf16 v[2:17], v[120:123], v[88:91], v[2:17]
	global_load_dwordx4 v[88:91], v[70:71], off offset:3584
	s_waitcnt vmcnt(15)
	v_mfma_f32_32x32x16_bf16 v[2:17], v[124:127], v[92:95], v[2:17]
	global_load_dwordx4 v[92:95], v[70:71], off offset:3616
	s_waitcnt vmcnt(15)
	v_mfma_f32_32x32x16_bf16 v[2:17], v[128:131], v[96:99], v[2:17]
	global_load_dwordx4 v[96:99], v[70:71], off offset:3648
	s_waitcnt vmcnt(15)
	v_mfma_f32_32x32x16_bf16 v[2:17], v[132:135], v[100:103], v[2:17]
	global_load_dwordx4 v[100:103], v[70:71], off offset:3680
	ds_read_b128 v[104:107], v69 offset:3584
	ds_read_b128 v[108:111], v69 offset:3616
	ds_read_b128 v[112:115], v69 offset:3648
	ds_read_b128 v[116:119], v69 offset:3680
	ds_read_b128 v[120:123], v69 offset:3712
	ds_read_b128 v[124:127], v69 offset:3744
	ds_read_b128 v[128:131], v69 offset:3776
	ds_read_b128 v[132:135], v69 offset:3808
	s_waitcnt lgkmcnt(8)
	s_waitcnt vmcnt(15)
	v_mfma_f32_32x32x16_bf16 v[2:17], v[136:139], v[168:171], v[2:17]
	global_load_dwordx4 v[168:171], v[70:71], off offset:3712
	s_waitcnt vmcnt(15)
	v_mfma_f32_32x32x16_bf16 v[2:17], v[140:143], v[172:175], v[2:17]
	global_load_dwordx4 v[172:175], v[70:71], off offset:3744
	s_waitcnt vmcnt(15)
	v_mfma_f32_32x32x16_bf16 v[2:17], v[144:147], v[176:179], v[2:17]
	global_load_dwordx4 v[176:179], v[70:71], off offset:3776
	s_waitcnt vmcnt(15)
	v_mfma_f32_32x32x16_bf16 v[2:17], v[148:151], v[180:183], v[2:17]
	global_load_dwordx4 v[180:183], v[70:71], off offset:3808
	s_waitcnt vmcnt(15)
	v_mfma_f32_32x32x16_bf16 v[2:17], v[152:155], v[184:187], v[2:17]
	global_load_dwordx4 v[184:187], v[70:71], off offset:3840
	s_waitcnt vmcnt(15)
	v_mfma_f32_32x32x16_bf16 v[2:17], v[156:159], v[188:191], v[2:17]
	global_load_dwordx4 v[188:191], v[70:71], off offset:3872
	s_waitcnt vmcnt(15)
	v_mfma_f32_32x32x16_bf16 v[2:17], v[160:163], v[192:195], v[2:17]
	global_load_dwordx4 v[192:195], v[70:71], off offset:3904
	s_waitcnt vmcnt(15)
	v_mfma_f32_32x32x16_bf16 v[2:17], v[164:167], v[196:199], v[2:17]
	global_load_dwordx4 v[196:199], v[70:71], off offset:3936
	ds_read_b128 v[136:139], v69 offset:3840
	ds_read_b128 v[140:143], v69 offset:3872
	ds_read_b128 v[144:147], v69 offset:3904
	ds_read_b128 v[148:151], v69 offset:3936
	ds_read_b128 v[152:155], v69 offset:3968
	ds_read_b128 v[156:159], v69 offset:4000
	ds_read_b128 v[160:163], v69 offset:4032
	ds_read_b128 v[164:167], v69 offset:4064
	s_waitcnt lgkmcnt(8)
	s_waitcnt vmcnt(15)
	v_mfma_f32_32x32x16_bf16 v[2:17], v[104:107], v[72:75], v[2:17]
	s_waitcnt vmcnt(14)
	v_mfma_f32_32x32x16_bf16 v[2:17], v[108:111], v[76:79], v[2:17]
	s_waitcnt vmcnt(13)
	v_mfma_f32_32x32x16_bf16 v[2:17], v[112:115], v[80:83], v[2:17]
	s_waitcnt vmcnt(12)
	v_mfma_f32_32x32x16_bf16 v[2:17], v[116:119], v[84:87], v[2:17]
	s_waitcnt vmcnt(11)
	v_mfma_f32_32x32x16_bf16 v[2:17], v[120:123], v[88:91], v[2:17]
	s_waitcnt vmcnt(10)
	v_mfma_f32_32x32x16_bf16 v[2:17], v[124:127], v[92:95], v[2:17]
	s_waitcnt vmcnt(9)
	v_mfma_f32_32x32x16_bf16 v[2:17], v[128:131], v[96:99], v[2:17]
	s_waitcnt vmcnt(8)
; __device__ __forceinline__ int crow(int r, int hi) { return (r & 3) + 8 * (r >> 2) + 4 * hi; }
; __device__ __forceinline__ v16f mfma32(v8s a, v8s b, v16f c) { return __builtin_amdgcn_mfma_f32_32x32x16_bf16(a, b, c, 0, 0, 0); }
; __device__ __forceinline__ float gelu_tanh(float x) {
;     const float u = 0.7978845608028654f * (x + 0.044715f * x * x * x);
;     const float t = 1.f - 2.f / (1.f + __expf(2.f * u));
;     return 0.5f * x * (1.f + t);
; }
; __device__ __forceinline__ void compress_unit(LAS unsigned char* lds, int u, const bf16_t* QKV, const float* pe_k, const float* pe_v,
;                                               const bf16_t* CW1  , const bf16_t* CW2  , bf16_t* KCMP, bf16_t* VCMP) {
;     ...
;         acc = mfma32(__builtin_bit_cast(v8s, aw), bfr, acc);
;     }
; #pragma unroll
;     for (int r = 0; r < 16; ++r) HID[crow(r, hi) * 264 + 32 * w + r32] = (bf16_t)(pkbf(gelu_tanh(acc[r]), 0.f) & 0xffffu);
	v_mfma_f32_32x32x16_bf16 v[2:17], v[132:135], v[100:103], v[2:17]
	s_waitcnt lgkmcnt(0)
	s_waitcnt vmcnt(7)
	v_mfma_f32_32x32x16_bf16 v[2:17], v[136:139], v[168:171], v[2:17]
	s_waitcnt vmcnt(6)
	v_mfma_f32_32x32x16_bf16 v[2:17], v[140:143], v[172:175], v[2:17]
	s_waitcnt vmcnt(5)
	v_mfma_f32_32x32x16_bf16 v[2:17], v[144:147], v[176:179], v[2:17]
	s_waitcnt vmcnt(4)
	v_mfma_f32_32x32x16_bf16 v[2:17], v[148:151], v[180:183], v[2:17]
	s_waitcnt vmcnt(3)
	v_mfma_f32_32x32x16_bf16 v[2:17], v[152:155], v[184:187], v[2:17]
	s_waitcnt vmcnt(2)
	v_mfma_f32_32x32x16_bf16 v[2:17], v[156:159], v[188:191], v[2:17]
	s_waitcnt vmcnt(1)
	v_mfma_f32_32x32x16_bf16 v[2:17], v[160:163], v[192:195], v[2:17]
	s_waitcnt vmcnt(0)
	v_mfma_f32_32x32x16_bf16 v[2:17], v[164:167], v[196:199], v[2:17]
	s_nop 10
	v_mul_f32_e32 v18, 0x3d372713, v2
	v_mul_f32_e32 v18, v2, v18
	v_fma_f32 v18, v2, v18, v2
	v_mul_f32_e32 v18, 0x3f4c422a, v18
	v_add_f32_e32 v18, v18, v18
	v_mul_f32_e32 v18, 0x3fb8aa3b, v18
	v_exp_f32_e32 v19, v18
	v_mul_f32_e32 v2, 0.5, v2
	v_lshlrev_b32_e32 v18, 2, v40
	v_add_f32_e32 v19, 1.0, v19
	v_div_scale_f32 v20, s[16:17], v19, v19, 2.0
	v_rcp_f32_e32 v21, v20
	s_lshl_b32 s16, s10, 1
	s_add_i32 s16, s16, 0
	v_lshl_add_u32 v22, v41, 1, s16
	v_fma_f32 v23, -v20, v21, 1.0
	v_fmac_f32_e32 v21, v23, v21
	v_div_scale_f32 v23, vcc, 2.0, v19, 2.0
	v_mul_f32_e32 v24, v23, v21
	v_fma_f32 v25, -v20, v24, v23
	v_fmac_f32_e32 v24, v25, v21
	v_fma_f32 v20, -v20, v24, v23
	v_div_fmas_f32 v20, v20, v21, v24
	v_div_fixup_f32 v19, v20, v19, 2.0
	v_mul_f32_e32 v20, 0x3d372713, v3
	v_mul_f32_e32 v20, v3, v20
	v_fma_f32 v20, v3, v20, v3
	v_mul_f32_e32 v20, 0x3f4c422a, v20
	v_add_f32_e32 v20, v20, v20
	v_mul_f32_e32 v20, 0x3fb8aa3b, v20
	v_exp_f32_e32 v20, v20
	v_sub_f32_e32 v19, 1.0, v19
	v_add_f32_e32 v19, 1.0, v19
	v_mul_f32_e32 v2, v2, v19
	v_add_f32_e32 v19, 1.0, v20
	v_div_scale_f32 v20, s[16:17], v19, v19, 2.0
	v_rcp_f32_e32 v21, v20
	s_movk_i32 s16, 0x840
	v_cvt_pk_bf16_f32 v2, v2, s0
	v_mad_u32_u24 v23, v40, s16, v22
	ds_write_b16 v23, v2
	v_fma_f32 v2, -v20, v21, 1.0
	v_fmac_f32_e32 v21, v2, v21
	v_div_scale_f32 v2, vcc, 2.0, v19, 2.0
	v_mul_f32_e32 v23, v2, v21
	v_fma_f32 v24, -v20, v23, v2
	v_fmac_f32_e32 v23, v24, v21
	v_fma_f32 v2, -v20, v23, v2
	v_div_fmas_f32 v2, v2, v21, v23
	v_div_fixup_f32 v2, v2, v19, 2.0
	v_mul_f32_e32 v19, 0x3d372713, v4
	v_mul_f32_e32 v19, v4, v19
	v_fma_f32 v19, v4, v19, v4
	v_mul_f32_e32 v19, 0x3f4c422a, v19
	v_add_f32_e32 v19, v19, v19
	v_mul_f32_e32 v19, 0x3fb8aa3b, v19
	v_exp_f32_e32 v19, v19
	v_sub_f32_e32 v2, 1.0, v2
	v_mul_f32_e32 v3, 0.5, v3
	v_add_f32_e32 v2, 1.0, v2
	v_mul_f32_e32 v2, v3, v2
	v_add_f32_e32 v3, 1.0, v19
	v_div_scale_f32 v19, s[16:17], v3, v3, 2.0
	v_rcp_f32_e32 v20, v19
	v_or_b32_e32 v21, 1, v18
	s_movk_i32 s16, 0x210
	v_cvt_pk_bf16_f32 v2, v2, s0
	v_mad_u32_u24 v22, v21, s16, v22
	ds_write_b16 v22, v2
	v_fma_f32 v2, -v19, v20, 1.0
	v_fmac_f32_e32 v20, v2, v20
	v_div_scale_f32 v2, vcc, 2.0, v3, 2.0
	v_mul_f32_e32 v23, v2, v20
	v_fma_f32 v24, -v19, v23, v2
	v_fmac_f32_e32 v23, v24, v20
	v_fma_f32 v2, -v19, v23, v2
	v_div_fmas_f32 v2, v2, v20, v23
	v_div_fixup_f32 v2, v2, v3, 2.0
	v_mul_f32_e32 v3, 0x3d372713, v5
	v_mul_f32_e32 v3, v5, v3
	v_fma_f32 v3, v5, v3, v5
	v_mul_f32_e32 v3, 0x3f4c422a, v3
	v_add_f32_e32 v3, v3, v3
	v_mul_f32_e32 v3, 0x3fb8aa3b, v3
	v_exp_f32_e32 v3, v3
	v_sub_f32_e32 v2, 1.0, v2
	v_mul_f32_e32 v4, 0.5, v4
	v_add_f32_e32 v2, 1.0, v2
	v_add_f32_e32 v3, 1.0, v3
	v_div_scale_f32 v19, s[16:17], v3, v3, 2.0
	v_rcp_f32_e32 v20, v19
	v_mul_f32_e32 v2, v4, v2
	v_cvt_pk_bf16_f32 v2, v2, s0
	ds_write_b16 v22, v2 offset:528
	v_fma_f32 v2, -v19, v20, 1.0
	v_fmac_f32_e32 v20, v2, v20
	v_div_scale_f32 v2, vcc, 2.0, v3, 2.0
	v_mul_f32_e32 v4, v2, v20
	v_fma_f32 v23, -v19, v4, v2
	v_fmac_f32_e32 v4, v23, v20
	v_fma_f32 v2, -v19, v4, v2
	v_div_fmas_f32 v2, v2, v20, v4
	v_div_fixup_f32 v2, v2, v3, 2.0
	v_mul_f32_e32 v3, 0x3d372713, v6
	v_mul_f32_e32 v3, v6, v3
	v_fma_f32 v3, v6, v3, v6
	v_mul_f32_e32 v3, 0x3f4c422a, v3
	v_add_f32_e32 v3, v3, v3
	v_mul_f32_e32 v3, 0x3fb8aa3b, v3
	v_exp_f32_e32 v3, v3
	v_mul_f32_e32 v4, 0.5, v5
	v_sub_f32_e32 v2, 1.0, v2
	v_add_f32_e32 v2, 1.0, v2
	v_add_f32_e32 v3, 1.0, v3
	v_div_scale_f32 v5, s[16:17], v3, v3, 2.0
	v_rcp_f32_e32 v19, v5
	v_mul_f32_e32 v2, v4, v2
	v_cvt_pk_bf16_f32 v2, v2, s0
	ds_write_b16 v22, v2 offset:1056
	v_fma_f32 v2, -v5, v19, 1.0
	v_fmac_f32_e32 v19, v2, v19
	v_div_scale_f32 v2, vcc, 2.0, v3, 2.0
	v_mul_f32_e32 v4, v2, v19
	v_fma_f32 v20, -v5, v4, v2
	v_fmac_f32_e32 v4, v20, v19
	v_fma_f32 v2, -v5, v4, v2
	v_div_fmas_f32 v2, v2, v19, v4
	v_div_fixup_f32 v2, v2, v3, 2.0
	v_mul_f32_e32 v3, 0x3d372713, v7
	v_mul_f32_e32 v3, v7, v3
	v_fma_f32 v3, v7, v3, v7
	v_mul_f32_e32 v3, 0x3f4c422a, v3
	v_add_f32_e32 v3, v3, v3
	v_mul_f32_e32 v3, 0x3fb8aa3b, v3
	v_exp_f32_e32 v3, v3
	v_sub_f32_e32 v2, 1.0, v2
	v_mul_f32_e32 v4, 0.5, v6
	v_add_f32_e32 v2, 1.0, v2
	v_add_f32_e32 v3, 1.0, v3
	v_div_scale_f32 v5, s[16:17], v3, v3, 2.0
	v_rcp_f32_e32 v6, v5
	v_mul_f32_e32 v2, v4, v2
	v_cvt_pk_bf16_f32 v2, v2, s0
	ds_write_b16 v22, v2 offset:3696
	v_fma_f32 v2, -v5, v6, 1.0
	v_fmac_f32_e32 v6, v2, v6
	v_div_scale_f32 v2, vcc, 2.0, v3, 2.0
	v_mul_f32_e32 v4, v2, v6
	v_fma_f32 v19, -v5, v4, v2
	v_fmac_f32_e32 v4, v19, v6
	v_fma_f32 v2, -v5, v4, v2
	v_div_fmas_f32 v2, v2, v6, v4
	v_div_fixup_f32 v2, v2, v3, 2.0
	v_mul_f32_e32 v3, 0x3d372713, v8
	v_mul_f32_e32 v3, v8, v3
	v_fma_f32 v3, v8, v3, v8
	v_mul_f32_e32 v3, 0x3f4c422a, v3
	v_add_f32_e32 v3, v3, v3
	v_mul_f32_e32 v3, 0x3fb8aa3b, v3
	v_exp_f32_e32 v3, v3
	v_sub_f32_e32 v2, 1.0, v2
	v_mul_f32_e32 v4, 0.5, v7
; __device__ __forceinline__ int crow(int r, int hi) { return (r & 3) + 8 * (r >> 2) + 4 * hi; }
; __device__ __forceinline__ float gelu_tanh(float x) {
;     const float u = 0.7978845608028654f * (x + 0.044715f * x * x * x);
;     const float t = 1.f - 2.f / (1.f + __expf(2.f * u));
;     return 0.5f * x * (1.f + t);
; }
; __device__ __forceinline__ void compress_unit(LAS unsigned char* lds, int u, const bf16_t* QKV, const float* pe_k, const float* pe_v,
;                                               const bf16_t* CW1  , const bf16_t* CW2  , bf16_t* KCMP, bf16_t* VCMP) {
;     ...
;     for (int r = 0; r < 16; ++r) HID[crow(r, hi) * 264 + 32 * w + r32] = (bf16_t)(pkbf(gelu_tanh(acc[r]), 0.f) & 0xffffu);
	v_add_f32_e32 v2, 1.0, v2
	v_add_f32_e32 v3, 1.0, v3
	v_div_scale_f32 v5, s[16:17], v3, v3, 2.0
	v_rcp_f32_e32 v6, v5
	v_mul_f32_e32 v2, v4, v2
	v_cvt_pk_bf16_f32 v2, v2, s0
	ds_write_b16 v22, v2 offset:4224
	v_fma_f32 v2, -v5, v6, 1.0
	v_fmac_f32_e32 v6, v2, v6
	v_div_scale_f32 v2, vcc, 2.0, v3, 2.0
	v_mul_f32_e32 v4, v2, v6
	v_fma_f32 v7, -v5, v4, v2
	v_fmac_f32_e32 v4, v7, v6
	v_fma_f32 v2, -v5, v4, v2
	v_div_fmas_f32 v2, v2, v6, v4
	v_div_fixup_f32 v2, v2, v3, 2.0
	v_mul_f32_e32 v3, 0x3d372713, v9
	v_mul_f32_e32 v3, v9, v3
	v_fma_f32 v3, v9, v3, v9
	v_mul_f32_e32 v3, 0x3f4c422a, v3
	v_add_f32_e32 v3, v3, v3
	v_mul_f32_e32 v3, 0x3fb8aa3b, v3
	v_exp_f32_e32 v3, v3
	v_sub_f32_e32 v2, 1.0, v2
	v_mul_f32_e32 v4, 0.5, v8
	v_add_f32_e32 v2, 1.0, v2
	v_add_f32_e32 v3, 1.0, v3
	v_div_scale_f32 v5, s[16:17], v3, v3, 2.0
	v_rcp_f32_e32 v6, v5
	v_mul_f32_e32 v2, v4, v2
	v_cvt_pk_bf16_f32 v2, v2, s0
	ds_write_b16 v22, v2 offset:4752
	v_fma_f32 v2, -v5, v6, 1.0
	v_fmac_f32_e32 v6, v2, v6
	v_div_scale_f32 v2, vcc, 2.0, v3, 2.0
	v_mul_f32_e32 v4, v2, v6
	v_fma_f32 v7, -v5, v4, v2
	v_fmac_f32_e32 v4, v7, v6
	v_fma_f32 v2, -v5, v4, v2
	v_div_fmas_f32 v2, v2, v6, v4
	v_div_fixup_f32 v2, v2, v3, 2.0
	v_mul_f32_e32 v3, 0x3d372713, v10
	v_mul_f32_e32 v3, v10, v3
	v_fma_f32 v3, v10, v3, v10
	v_mul_f32_e32 v3, 0x3f4c422a, v3
	v_add_f32_e32 v3, v3, v3
	v_mul_f32_e32 v3, 0x3fb8aa3b, v3
	v_exp_f32_e32 v3, v3
	v_sub_f32_e32 v2, 1.0, v2
	v_mul_f32_e32 v4, 0.5, v9
	v_add_f32_e32 v2, 1.0, v2
	v_add_f32_e32 v3, 1.0, v3
	v_div_scale_f32 v5, s[16:17], v3, v3, 2.0
	v_rcp_f32_e32 v6, v5
	v_mul_f32_e32 v2, v4, v2
	v_cvt_pk_bf16_f32 v2, v2, s0
	ds_write_b16 v22, v2 offset:5280
	v_fma_f32 v2, -v5, v6, 1.0
	v_fmac_f32_e32 v6, v2, v6
	v_div_scale_f32 v2, vcc, 2.0, v3, 2.0
	v_mul_f32_e32 v4, v2, v6
	v_fma_f32 v7, -v5, v4, v2
	v_fmac_f32_e32 v4, v7, v6
	v_fma_f32 v2, -v5, v4, v2
	v_div_fmas_f32 v2, v2, v6, v4
	v_div_fixup_f32 v2, v2, v3, 2.0
	v_mul_f32_e32 v3, 0x3d372713, v11
	v_mul_f32_e32 v3, v11, v3
	v_fma_f32 v3, v11, v3, v11
	v_mul_f32_e32 v3, 0x3f4c422a, v3
	v_add_f32_e32 v3, v3, v3
	v_mul_f32_e32 v3, 0x3fb8aa3b, v3
	v_exp_f32_e32 v3, v3
	v_sub_f32_e32 v2, 1.0, v2
	v_mul_f32_e32 v4, 0.5, v10
	v_add_f32_e32 v2, 1.0, v2
	v_add_f32_e32 v3, 1.0, v3
	v_div_scale_f32 v5, s[16:17], v3, v3, 2.0
	v_rcp_f32_e32 v6, v5
	v_mul_f32_e32 v2, v4, v2
	v_cvt_pk_bf16_f32 v2, v2, s0
	ds_write_b16 v22, v2 offset:7920
	v_fma_f32 v2, -v5, v6, 1.0
	v_fmac_f32_e32 v6, v2, v6
	v_div_scale_f32 v2, vcc, 2.0, v3, 2.0
	v_mul_f32_e32 v4, v2, v6
	v_fma_f32 v7, -v5, v4, v2
	v_fmac_f32_e32 v4, v7, v6
	v_fma_f32 v2, -v5, v4, v2
	v_div_fmas_f32 v2, v2, v6, v4
	v_div_fixup_f32 v2, v2, v3, 2.0
	v_mul_f32_e32 v3, 0x3d372713, v12
	v_mul_f32_e32 v3, v12, v3
	v_fma_f32 v3, v12, v3, v12
	v_mul_f32_e32 v3, 0x3f4c422a, v3
	v_add_f32_e32 v3, v3, v3
	v_mul_f32_e32 v3, 0x3fb8aa3b, v3
	v_exp_f32_e32 v3, v3
	v_sub_f32_e32 v2, 1.0, v2
	v_mul_f32_e32 v4, 0.5, v11
	v_add_f32_e32 v2, 1.0, v2
	v_add_f32_e32 v3, 1.0, v3
	v_div_scale_f32 v5, s[16:17], v3, v3, 2.0
	v_rcp_f32_e32 v6, v5
	v_mul_f32_e32 v2, v4, v2
	v_cvt_pk_bf16_f32 v2, v2, s0
	ds_write_b16 v22, v2 offset:8448
	v_fma_f32 v2, -v5, v6, 1.0
	v_fmac_f32_e32 v6, v2, v6
	v_div_scale_f32 v2, vcc, 2.0, v3, 2.0
	v_mul_f32_e32 v4, v2, v6
	v_fma_f32 v7, -v5, v4, v2
	v_fmac_f32_e32 v4, v7, v6
	v_fma_f32 v2, -v5, v4, v2
	v_div_fmas_f32 v2, v2, v6, v4
	v_div_fixup_f32 v2, v2, v3, 2.0
	v_mul_f32_e32 v3, 0x3d372713, v13
	v_mul_f32_e32 v3, v13, v3
	v_fma_f32 v3, v13, v3, v13
	v_mul_f32_e32 v3, 0x3f4c422a, v3
	v_add_f32_e32 v3, v3, v3
	v_mul_f32_e32 v3, 0x3fb8aa3b, v3
	v_exp_f32_e32 v3, v3
	v_sub_f32_e32 v2, 1.0, v2
	v_mul_f32_e32 v4, 0.5, v12
	v_add_f32_e32 v2, 1.0, v2
	v_add_f32_e32 v3, 1.0, v3
	v_div_scale_f32 v5, s[16:17], v3, v3, 2.0
	v_rcp_f32_e32 v6, v5
	v_mul_f32_e32 v2, v4, v2
	v_cvt_pk_bf16_f32 v2, v2, s0
	ds_write_b16 v22, v2 offset:8976
	v_fma_f32 v2, -v5, v6, 1.0
	v_fmac_f32_e32 v6, v2, v6
	v_div_scale_f32 v2, vcc, 2.0, v3, 2.0
	v_mul_f32_e32 v4, v2, v6
	v_fma_f32 v7, -v5, v4, v2
	v_fmac_f32_e32 v4, v7, v6
	v_fma_f32 v2, -v5, v4, v2
	v_div_fmas_f32 v2, v2, v6, v4
	v_div_fixup_f32 v2, v2, v3, 2.0
	v_mul_f32_e32 v3, 0x3d372713, v14
	v_mul_f32_e32 v3, v14, v3
	v_fma_f32 v3, v14, v3, v14
	v_mul_f32_e32 v3, 0x3f4c422a, v3
	v_add_f32_e32 v3, v3, v3
	v_mul_f32_e32 v3, 0x3fb8aa3b, v3
	v_exp_f32_e32 v3, v3
	v_sub_f32_e32 v2, 1.0, v2
	v_mul_f32_e32 v4, 0.5, v13
	v_add_f32_e32 v2, 1.0, v2
	v_add_f32_e32 v3, 1.0, v3
	v_div_scale_f32 v5, s[16:17], v3, v3, 2.0
	v_rcp_f32_e32 v6, v5
	v_mul_f32_e32 v2, v4, v2
	v_cvt_pk_bf16_f32 v2, v2, s0
	ds_write_b16 v22, v2 offset:9504
	v_fma_f32 v2, -v5, v6, 1.0
	v_fmac_f32_e32 v6, v2, v6
	v_div_scale_f32 v2, vcc, 2.0, v3, 2.0
	v_mul_f32_e32 v4, v2, v6
	v_fma_f32 v7, -v5, v4, v2
	v_fmac_f32_e32 v4, v7, v6
	v_fma_f32 v2, -v5, v4, v2
	v_div_fmas_f32 v2, v2, v6, v4
	v_div_fixup_f32 v2, v2, v3, 2.0
	v_mul_f32_e32 v3, 0x3d372713, v15
	v_mul_f32_e32 v3, v15, v3
	v_fma_f32 v3, v15, v3, v15
	v_mul_f32_e32 v3, 0x3f4c422a, v3
	v_add_f32_e32 v3, v3, v3
	v_mul_f32_e32 v3, 0x3fb8aa3b, v3
	v_exp_f32_e32 v3, v3
	v_sub_f32_e32 v2, 1.0, v2
	v_mul_f32_e32 v4, 0.5, v14
	v_add_f32_e32 v2, 1.0, v2
	v_add_f32_e32 v3, 1.0, v3
	v_div_scale_f32 v5, s[16:17], v3, v3, 2.0
	v_rcp_f32_e32 v6, v5
	v_mul_f32_e32 v2, v4, v2
	v_cvt_pk_bf16_f32 v2, v2, s0
	ds_write_b16 v22, v2 offset:12144
	v_fma_f32 v2, -v5, v6, 1.0
	v_fmac_f32_e32 v6, v2, v6
	v_div_scale_f32 v2, vcc, 2.0, v3, 2.0
	v_mul_f32_e32 v4, v2, v6
	v_fma_f32 v7, -v5, v4, v2
	v_fmac_f32_e32 v4, v7, v6
	v_fma_f32 v2, -v5, v4, v2
	v_div_fmas_f32 v2, v2, v6, v4
	v_div_fixup_f32 v2, v2, v3, 2.0
	v_mul_f32_e32 v3, 0x3d372713, v16
; __device__ __forceinline__ int crow(int r, int hi) { return (r & 3) + 8 * (r >> 2) + 4 * hi; }
; __device__ __forceinline__ float gelu_tanh(float x) {
;     const float u = 0.7978845608028654f * (x + 0.044715f * x * x * x);
;     const float t = 1.f - 2.f / (1.f + __expf(2.f * u));
;     return 0.5f * x * (1.f + t);
; }
; __device__ __forceinline__ void compress_unit(LAS unsigned char* lds, int u, const bf16_t* QKV, const float* pe_k, const float* pe_v,
;                                               const bf16_t* CW1  , const bf16_t* CW2  , bf16_t* KCMP, bf16_t* VCMP) {
;     ...
;     for (int r = 0; r < 16; ++r) HID[crow(r, hi) * 264 + 32 * w + r32] = (bf16_t)(pkbf(gelu_tanh(acc[r]), 0.f) & 0xffffu);
;     __syncthreads();
;     if (w < 2) {
	v_mul_f32_e32 v3, v16, v3
	v_fma_f32 v3, v16, v3, v16
	v_mul_f32_e32 v3, 0x3f4c422a, v3
	v_add_f32_e32 v3, v3, v3
	v_mul_f32_e32 v3, 0x3fb8aa3b, v3
	v_exp_f32_e32 v3, v3
	v_sub_f32_e32 v2, 1.0, v2
	v_mul_f32_e32 v4, 0.5, v15
	v_add_f32_e32 v2, 1.0, v2
	v_add_f32_e32 v3, 1.0, v3
	v_div_scale_f32 v5, s[16:17], v3, v3, 2.0
	v_rcp_f32_e32 v6, v5
	v_mul_f32_e32 v2, v4, v2
	v_cvt_pk_bf16_f32 v2, v2, s0
	ds_write_b16 v22, v2 offset:12672
	v_fma_f32 v2, -v5, v6, 1.0
	v_fmac_f32_e32 v6, v2, v6
	v_div_scale_f32 v2, vcc, 2.0, v3, 2.0
	v_mul_f32_e32 v4, v2, v6
	v_fma_f32 v7, -v5, v4, v2
	v_fmac_f32_e32 v4, v7, v6
	v_fma_f32 v2, -v5, v4, v2
	v_div_fmas_f32 v2, v2, v6, v4
	v_div_fixup_f32 v2, v2, v3, 2.0
	v_mul_f32_e32 v3, 0x3d372713, v17
	v_mul_f32_e32 v3, v17, v3
	v_fma_f32 v3, v17, v3, v17
	v_mul_f32_e32 v3, 0x3f4c422a, v3
	v_add_f32_e32 v3, v3, v3
	v_mul_f32_e32 v3, 0x3fb8aa3b, v3
	v_exp_f32_e32 v3, v3
	v_sub_f32_e32 v2, 1.0, v2
	v_mul_f32_e32 v4, 0.5, v16
	v_add_f32_e32 v2, 1.0, v2
	v_add_f32_e32 v3, 1.0, v3
	v_div_scale_f32 v5, s[16:17], v3, v3, 2.0
	v_rcp_f32_e32 v6, v5
	v_mul_f32_e32 v2, v4, v2
	v_cvt_pk_bf16_f32 v2, v2, s0
	ds_write_b16 v22, v2 offset:13200
	v_fma_f32 v2, -v5, v6, 1.0
	v_fmac_f32_e32 v6, v2, v6
	v_div_scale_f32 v2, vcc, 2.0, v3, 2.0
	v_mul_f32_e32 v4, v2, v6
	v_fma_f32 v7, -v5, v4, v2
	v_fmac_f32_e32 v4, v7, v6
	v_fma_f32 v2, -v5, v4, v2
	v_div_fmas_f32 v2, v2, v6, v4
	v_div_fixup_f32 v2, v2, v3, 2.0
	v_sub_f32_e32 v2, 1.0, v2
	v_mul_f32_e32 v3, 0.5, v17
	v_add_f32_e32 v2, 1.0, v2
	v_mul_f32_e32 v2, v3, v2
	v_cvt_pk_bf16_f32 v2, v2, s0
	s_cmp_lt_i32 s29, 2
	ds_write_b16 v22, v2 offset:13728
	s_waitcnt lgkmcnt(0)
	s_barrier
	s_cbranch_scc0 .LBB0_410
; #define LAS __attribute__((address_space(3)))
; __device__ __forceinline__ int crow(int r, int hi) { return (r & 3) + 8 * (r >> 2) + 4 * hi; }
; __device__ __forceinline__ v16f mfma32(v8s a, v8s b, v16f c) { return __builtin_amdgcn_mfma_f32_32x32x16_bf16(a, b, c, 0, 0, 0); }
; __device__ __forceinline__ void compress_unit(LAS unsigned char* lds, int u, const bf16_t* QKV, const float* pe_k, const float* pe_v,
;                                               const bf16_t* CW1  , const bf16_t* CW2  , bf16_t* KCMP, bf16_t* VCMP) {
;     ...
;     if (w < 2) {
;         v16f o;
; #pragma unroll
;         for (int r = 0; r < 16; ++r) o[r] = 0.f;
;         const bf16_t* B2 = W2 + (size_t)(32 * w + r32) * 256 + hi * 8;
; #pragma unroll
;         for (int st = 0; st < 16; ++st) {
;             const v8s af = *(const LAS v8s*)(HID + r32 * 264 + st * 16 + hi * 8);
;             const v8s bfr = *(const v8s*)(B2 + st * 16);
;             o = mfma32(af, bfr, o);
;         }
; #pragma unroll
;         for (int r = 0; r < 16; ++r) { const int nl = crow(r, hi); const bool valid = (ch * 32 + nl) < 255;
;             OUT[(size_t)nl * 64 + 32 * w + r32] = valid ? (bf16_t)(pkbf(o[r], 0.f) & 0xffffu) : (bf16_t)0; }
;     }
	s_and_b32 s16, s28, 1
	s_lshl_b32 s11, s11, 9
	s_lshl_b32 s16, s16, 8
	s_or_b32 s11, s11, s16
	s_or_b32 s11, s11, s27
	s_lshl_b64 s[12:13], s[12:13], 15
	s_and_b64 s[14:15], s[14:15], exec
	s_cselect_b32 s16, s22, s24
	s_cselect_b32 s17, s21, s23
	s_add_u32 s14, s19, s12
	s_addc_u32 s15, s20, s13
	v_lshlrev_b64 v[2:3], 9, v[34:35]
	v_lshl_add_u64 v[2:3], s[14:15], 0, v[2:3]
	v_lshlrev_b32_e32 v30, 7, v18
	v_or_b32_e32 v20, 27, v18
	v_lshl_add_u64 v[18:19], v[2:3], 0, v[0:1]
	v_mul_u32_u24_e32 v2, 0x210, v41
	v_add3_u32 v0, 0, v2, v0
	global_load_dwordx4 v[64:67], v[18:19], off
	global_load_dwordx4 v[68:71], v[18:19], off offset:32
	global_load_dwordx4 v[72:75], v[18:19], off offset:64
	global_load_dwordx4 v[76:79], v[18:19], off offset:96
	global_load_dwordx4 v[80:83], v[18:19], off offset:128
	global_load_dwordx4 v[84:87], v[18:19], off offset:160
	global_load_dwordx4 v[88:91], v[18:19], off offset:192
	global_load_dwordx4 v[92:95], v[18:19], off offset:224
	global_load_dwordx4 v[96:99], v[18:19], off offset:256
	global_load_dwordx4 v[100:103], v[18:19], off offset:288
	global_load_dwordx4 v[104:107], v[18:19], off offset:320
	global_load_dwordx4 v[108:111], v[18:19], off offset:352
	global_load_dwordx4 v[112:115], v[18:19], off offset:384
	global_load_dwordx4 v[116:119], v[18:19], off offset:416
	global_load_dwordx4 v[120:123], v[18:19], off offset:448
	global_load_dwordx4 v[124:127], v[18:19], off offset:480
	ds_read_b128 v[128:131], v0
	ds_read_b128 v[132:135], v0 offset:32
	ds_read_b128 v[136:139], v0 offset:64
	ds_read_b128 v[140:143], v0 offset:96
	ds_read_b128 v[144:147], v0 offset:128
	ds_read_b128 v[148:151], v0 offset:160
	ds_read_b128 v[152:155], v0 offset:192
	ds_read_b128 v[156:159], v0 offset:224
	ds_read_b128 v[160:163], v0 offset:256
	ds_read_b128 v[164:167], v0 offset:288
	ds_read_b128 v[168:171], v0 offset:320
	ds_read_b128 v[172:175], v0 offset:352
	ds_read_b128 v[176:179], v0 offset:384
	ds_read_b128 v[180:183], v0 offset:416
	ds_read_b128 v[184:187], v0 offset:448
	ds_read_b128 v[188:191], v0 offset:480
	s_lshl_b32 s11, s11, 7
	s_add_u32 s12, s17, s11
	s_addc_u32 s13, s16, 0
	s_ashr_i32 s11, s10, 31
	s_lshl_b64 s[10:11], s[10:11], 1
	s_add_u32 s10, s12, s10
	s_addc_u32 s11, s13, s11
	v_lshlrev_b32_e32 v0, 1, v41
	v_lshl_add_u64 v[18:19], s[10:11], 0, v[0:1]
	v_lshlrev_b32_e32 v0, 9, v40
	s_movk_i32 s10, 0xff
	s_waitcnt lgkmcnt(0)
	s_waitcnt vmcnt(15)
	v_mfma_f32_32x32x16_bf16 v[2:17], v[128:131], v[64:67], 0
	s_waitcnt vmcnt(14)
	v_mfma_f32_32x32x16_bf16 v[2:17], v[132:135], v[68:71], v[2:17]
	s_waitcnt vmcnt(13)
	v_mfma_f32_32x32x16_bf16 v[2:17], v[136:139], v[72:75], v[2:17]
	s_waitcnt vmcnt(12)
	v_mfma_f32_32x32x16_bf16 v[2:17], v[140:143], v[76:79], v[2:17]
	s_waitcnt vmcnt(11)
	v_mfma_f32_32x32x16_bf16 v[2:17], v[144:147], v[80:83], v[2:17]
	s_waitcnt vmcnt(10)
	v_mfma_f32_32x32x16_bf16 v[2:17], v[148:151], v[84:87], v[2:17]
	s_waitcnt vmcnt(9)
	v_mfma_f32_32x32x16_bf16 v[2:17], v[152:155], v[88:91], v[2:17]
	s_waitcnt vmcnt(8)
	v_mfma_f32_32x32x16_bf16 v[2:17], v[156:159], v[92:95], v[2:17]
	s_waitcnt vmcnt(7)
	v_mfma_f32_32x32x16_bf16 v[2:17], v[160:163], v[96:99], v[2:17]
	s_waitcnt vmcnt(6)
	v_mfma_f32_32x32x16_bf16 v[2:17], v[164:167], v[100:103], v[2:17]
	s_waitcnt vmcnt(5)
	v_mfma_f32_32x32x16_bf16 v[2:17], v[168:171], v[104:107], v[2:17]
	s_waitcnt vmcnt(4)
	v_mfma_f32_32x32x16_bf16 v[2:17], v[172:175], v[108:111], v[2:17]
	s_waitcnt vmcnt(3)
	v_mfma_f32_32x32x16_bf16 v[2:17], v[176:179], v[112:115], v[2:17]
	s_waitcnt vmcnt(2)
	v_mfma_f32_32x32x16_bf16 v[2:17], v[180:183], v[116:119], v[2:17]
	s_waitcnt vmcnt(1)
	v_mfma_f32_32x32x16_bf16 v[2:17], v[184:187], v[120:123], v[2:17]
	s_waitcnt vmcnt(0)
	v_mfma_f32_32x32x16_bf16 v[2:17], v[188:191], v[124:127], v[2:17]
	v_lshl_add_u64 v[22:23], v[18:19], 0, v[0:1]
	v_lshlrev_b32_e32 v0, 7, v21
	s_nop 9
	v_cvt_pk_bf16_f32 v2, v2, s0
	global_store_short v[22:23], v2, off
	v_cvt_pk_bf16_f32 v22, v3, s0
	v_lshl_add_u64 v[2:3], v[18:19], 0, v[0:1]
	v_or_b32_e32 v0, 0x100, v30
	global_store_short v[2:3], v22, off
	v_cvt_pk_bf16_f32 v4, v4, s0
	v_lshl_add_u64 v[2:3], v[18:19], 0, v[0:1]
	v_or_b32_e32 v0, 0x180, v30
	global_store_short v[2:3], v4, off
	v_cvt_pk_bf16_f32 v4, v5, s0
	v_lshl_add_u64 v[2:3], v[18:19], 0, v[0:1]
	v_or_b32_e32 v0, 0x400, v30
	global_store_short v[2:3], v4, off
	v_cvt_pk_bf16_f32 v4, v6, s0
	v_lshl_add_u64 v[2:3], v[18:19], 0, v[0:1]
	v_or_b32_e32 v0, 0x480, v30
	global_store_short v[2:3], v4, off
	v_cvt_pk_bf16_f32 v4, v7, s0
	v_lshl_add_u64 v[2:3], v[18:19], 0, v[0:1]
	v_or_b32_e32 v0, 0x500, v30
	global_store_short v[2:3], v4, off
	v_cvt_pk_bf16_f32 v4, v8, s0
	v_lshl_add_u64 v[2:3], v[18:19], 0, v[0:1]
	v_or_b32_e32 v0, 0x580, v30
	global_store_short v[2:3], v4, off
	v_cvt_pk_bf16_f32 v4, v9, s0
	v_lshl_add_u64 v[2:3], v[18:19], 0, v[0:1]
	v_or_b32_e32 v0, 0x800, v30
	global_store_short v[2:3], v4, off
	v_cvt_pk_bf16_f32 v4, v10, s0
	v_lshl_add_u64 v[2:3], v[18:19], 0, v[0:1]
	v_or_b32_e32 v0, 0x880, v30
	global_store_short v[2:3], v4, off
	v_cvt_pk_bf16_f32 v4, v11, s0
	v_lshl_add_u64 v[2:3], v[18:19], 0, v[0:1]
	v_or_b32_e32 v0, 0x900, v30
	global_store_short v[2:3], v4, off
	v_cvt_pk_bf16_f32 v4, v12, s0
	v_lshl_add_u64 v[2:3], v[18:19], 0, v[0:1]
	v_or_b32_e32 v0, 0x980, v30
	global_store_short v[2:3], v4, off
	v_cvt_pk_bf16_f32 v4, v13, s0
	v_lshl_add_u64 v[2:3], v[18:19], 0, v[0:1]
	v_or_b32_e32 v0, 0xc00, v30
	global_store_short v[2:3], v4, off
	v_cvt_pk_bf16_f32 v4, v14, s0
	v_lshl_add_u64 v[2:3], v[18:19], 0, v[0:1]
	v_or_b32_e32 v0, 0xc80, v30
	global_store_short v[2:3], v4, off
	v_cvt_pk_bf16_f32 v4, v15, s0
	v_lshl_add_u64 v[2:3], v[18:19], 0, v[0:1]
	v_or_b32_e32 v0, 0xd00, v30
	global_store_short v[2:3], v4, off
	v_cvt_pk_bf16_f32 v4, v16, s0
	v_lshl_add_u64 v[2:3], v[18:19], 0, v[0:1]
	v_or_b32_e32 v0, s27, v20
	global_store_short v[2:3], v4, off
	v_cvt_pk_bf16_f32 v2, v17, s0
	v_cmp_ne_u32_e32 vcc, s10, v0
	v_lshlrev_b32_e32 v0, 7, v20
	s_nop 0
	v_cndmask_b32_e32 v4, 0, v2, vcc
	v_lshl_add_u64 v[2:3], v[18:19], 0, v[0:1]
	global_store_short v[2:3], v4, off
	s_branch .LBB0_410
